# wave reductions: last four (or three) butterfly steps via DPP row_mirror/row_half_mirror/quad_perm adds instead of ds_bpermute round trips (phases 0,5,7,12)
# speedup vs baseline: 1.0377x; 1.0043x over previous
.LBB0_15:
	v_ashrrev_i32_e32 v1, 31, v0
	v_lshlrev_b64 v[2:3], 12, v[0:1]
	v_lshl_add_u64 v[2:3], v[70:71], 0, v[2:3]
	global_load_dwordx2 v[64:65], v[2:3], off offset:512 nt
	global_load_dwordx2 v[66:67], v[2:3], off offset:1024 nt
	global_load_dwordx2 v[86:87], v[2:3], off offset:1536 nt
	v_add_u32_e32 v181, s55, v0
	global_load_dwordx2 v[88:89], v[2:3], off offset:2048 nt
	global_load_dwordx2 v[90:91], v[2:3], off offset:2560 nt
	v_cmp_gt_i32_e32 vcc, s76, v181
	s_waitcnt vmcnt(4)
	v_lshlrev_b32_e32 v162, 16, v64
	v_cndmask_b32_e32 v4, v0, v181, vcc
	v_ashrrev_i32_e32 v5, 31, v4
	v_lshlrev_b64 v[6:7], 12, v[4:5]
	v_lshlrev_b64 v[0:1], 13, v[0:1]
	v_lshl_add_u64 v[8:9], v[70:71], 0, v[6:7]
	v_lshl_add_u64 v[84:85], v[80:81], 0, v[0:1]
	global_load_dwordx2 v[92:93], v[8:9], off offset:512 nt
	global_load_dwordx2 v[94:95], v[8:9], off offset:1024 nt
	global_load_dwordx2 v[96:97], v[8:9], off offset:1536 nt
	global_load_dwordx2 v[100:101], v[8:9], off offset:2048 nt
	global_load_dwordx2 v[102:103], v[8:9], off offset:2560 nt
	global_load_dwordx2 v[170:171], v[2:3], off nt
	global_load_dwordx2 v[176:177], v[8:9], off nt
	global_load_dwordx4 v[56:59], v[84:85], off nt
	global_load_dwordx4 v[48:51], v[84:85], off offset:1024 nt
	global_load_dwordx4 v[40:43], v[84:85], off offset:2048 nt
	global_load_dwordx4 v[32:35], v[84:85], off offset:3072 nt
	global_load_dwordx2 v[110:111], v[2:3], off offset:3072 nt
	global_load_dwordx2 v[178:179], v[8:9], off offset:3072 nt
	global_load_dwordx2 v[182:183], v[2:3], off offset:3584 nt
	v_lshlrev_b64 v[0:1], 13, v[4:5]
	v_add_co_u32_e64 v4, s[10:11], s29, v84
	v_lshl_add_u64 v[82:83], v[80:81], 0, v[0:1]
	s_nop 0
	v_addc_co_u32_e64 v5, s[10:11], 0, v85, s[10:11]
	v_add_co_u32_e64 v0, s[10:11], s29, v82
	global_load_dwordx4 v[28:31], v[4:5], off nt
	global_load_dwordx4 v[20:23], v[4:5], off offset:1024 nt
	global_load_dwordx4 v[12:15], v[4:5], off offset:2048 nt
	s_nop 0
	global_load_dwordx4 v[4:7], v[4:5], off offset:3072 nt
	s_nop 0
	global_load_dwordx4 v[60:63], v[82:83], off nt
	global_load_dwordx4 v[52:55], v[82:83], off offset:1024 nt
	global_load_dwordx4 v[44:47], v[82:83], off offset:2048 nt
	global_load_dwordx4 v[36:39], v[82:83], off offset:3072 nt
	v_addc_co_u32_e64 v1, s[10:11], 0, v83, s[10:11]
	global_load_dwordx2 v[192:193], v[8:9], off offset:3584 nt
	global_load_dwordx4 v[24:27], v[0:1], off nt
	global_load_dwordx4 v[16:19], v[0:1], off offset:1024 nt
	s_nop 0
	global_load_dwordx4 v[8:11], v[0:1], off offset:2048 nt
	s_nop 0
	global_load_dwordx4 v[0:3], v[0:1], off offset:3072 nt
	s_waitcnt vmcnt(28)
	v_and_b32_e32 v99, 0xffff0000, v88
	s_waitcnt vmcnt(27)
	v_lshlrev_b32_e32 v98, 16, v90
	v_and_b32_e32 v117, 0xffff0000, v90
	v_mov_b32_e32 v116, v99
	v_and_b32_e32 v167, 0xffff0000, v64
	v_lshlrev_b32_e32 v164, 16, v65
	v_and_b32_e32 v169, 0xffff0000, v65
	v_lshlrev_b32_e32 v104, 16, v88
	v_lshlrev_b32_e32 v122, 16, v91
	v_mov_b32_e32 v105, v98
	v_pk_mul_f32 v[64:65], v[116:117], v[116:117]
	v_lshlrev_b32_e32 v108, 16, v89
	v_and_b32_e32 v125, 0xffff0000, v89
	v_pk_fma_f32 v[64:65], v[104:105], v[104:105], v[64:65]
	v_mov_b32_e32 v109, v122
	v_and_b32_e32 v133, 0xffff0000, v91
	v_pk_fma_f32 v[64:65], v[108:109], v[108:109], v[64:65]
	v_mov_b32_e32 v132, v125
	v_pk_fma_f32 v[194:195], v[132:133], v[132:133], v[64:65]
	v_lshlrev_b32_e32 v134, 16, v86
	v_and_b32_e32 v139, 0xffff0000, v86
	v_lshlrev_b32_e32 v136, 16, v87
	v_and_b32_e32 v141, 0xffff0000, v87
	v_lshlrev_b32_e32 v150, 16, v66
	v_and_b32_e32 v155, 0xffff0000, v66
	v_lshlrev_b32_e32 v152, 16, v67
	v_and_b32_e32 v157, 0xffff0000, v67
	v_mov_b32_e32 v175, v162
	v_mov_b32_e32 v173, v164
	v_mov_b32_e32 v161, v150
	v_mov_b32_e32 v159, v152
	v_mov_b32_e32 v145, v134
	v_mov_b32_e32 v143, v136
	s_waitcnt vmcnt(26)
	v_lshlrev_b32_e32 v174, 16, v92
	s_waitcnt vmcnt(25)
	v_lshlrev_b32_e32 v160, 16, v94
	s_waitcnt vmcnt(24)
	v_lshlrev_b32_e32 v144, 16, v96
	s_waitcnt vmcnt(23)
	v_and_b32_e32 v121, 0xffff0000, v100
	s_waitcnt vmcnt(22)
	v_lshlrev_b32_e32 v116, 16, v102
	v_and_b32_e32 v129, 0xffff0000, v102
	v_mov_b32_e32 v128, v121
	v_lshlrev_b32_e32 v114, 16, v100
	v_lshlrev_b32_e32 v120, 16, v103
	v_mov_b32_e32 v115, v116
	v_pk_mul_f32 v[64:65], v[128:129], v[128:129]
	v_lshlrev_b32_e32 v112, 16, v101
	v_and_b32_e32 v123, 0xffff0000, v101
	v_pk_fma_f32 v[64:65], v[114:115], v[114:115], v[64:65]
	v_mov_b32_e32 v113, v120
	s_waitcnt vmcnt(15)
	v_and_b32_e32 v119, 0xffff0000, v110
	v_and_b32_e32 v147, 0xffff0000, v96
	v_and_b32_e32 v131, 0xffff0000, v103
	v_pk_fma_f32 v[64:65], v[112:113], v[112:113], v[64:65]
	v_mov_b32_e32 v130, v123
	s_waitcnt vmcnt(13)
	v_lshlrev_b32_e32 v96, 16, v182
	v_and_b32_e32 v87, 0xffff0000, v182
	v_mov_b32_e32 v86, v119
	v_and_b32_e32 v135, 0xffff0000, v94
	v_pk_fma_f32 v[196:197], v[130:131], v[130:131], v[64:65]
	v_lshlrev_b32_e32 v106, 16, v110
	v_lshlrev_b32_e32 v94, 16, v183
	v_mov_b32_e32 v107, v96
	v_pk_mul_f32 v[64:65], v[86:87], v[86:87]
	v_lshlrev_b32_e32 v158, 16, v95
	v_and_b32_e32 v137, 0xffff0000, v95
	v_lshlrev_b32_e32 v110, 16, v111
	v_and_b32_e32 v127, 0xffff0000, v111
	v_and_b32_e32 v95, 0xffff0000, v178
	v_pk_fma_f32 v[64:65], v[106:107], v[106:107], v[64:65]
	v_mov_b32_e32 v111, v94
	v_and_b32_e32 v89, 0xffff0000, v183
	v_pk_fma_f32 v[64:65], v[110:111], v[110:111], v[64:65]
	v_mov_b32_e32 v88, v127
	s_waitcnt vmcnt(4)
	v_lshlrev_b32_e32 v86, 16, v192
	v_and_b32_e32 v91, 0xffff0000, v192
	v_mov_b32_e32 v90, v95
	v_lshlrev_b32_e32 v100, 16, v178
	v_pk_fma_f32 v[182:183], v[88:89], v[88:89], v[64:65]
	v_lshlrev_b32_e32 v88, 16, v193
	v_mov_b32_e32 v101, v86
	v_pk_mul_f32 v[64:65], v[90:91], v[90:91]
	v_lshlrev_b32_e32 v142, 16, v97
	v_and_b32_e32 v149, 0xffff0000, v97
	v_lshlrev_b32_e32 v102, 16, v179
	v_and_b32_e32 v97, 0xffff0000, v179
	v_pk_fma_f32 v[64:65], v[100:101], v[100:101], v[64:65]
	v_mov_b32_e32 v103, v88
	v_and_b32_e32 v151, 0xffff0000, v92
	v_lshlrev_b32_e32 v172, 16, v93
	v_and_b32_e32 v153, 0xffff0000, v93
	v_and_b32_e32 v93, 0xffff0000, v193
	v_pk_fma_f32 v[64:65], v[102:103], v[102:103], v[64:65]
	v_mov_b32_e32 v92, v97
	v_pk_fma_f32 v[192:193], v[92:93], v[92:93], v[64:65]
	v_and_b32_e32 v101, 0xffff0000, v176
	v_and_b32_e32 v199, 0xffff0000, v170
	v_lshlrev_b32_e32 v198, 16, v170
	v_mov_b32_e32 v166, v151
	v_mov_b32_e32 v206, v101
	v_mov_b32_e32 v207, v199
	v_lshlrev_b32_e32 v178, 16, v176
	v_lshlrev_b32_e32 v200, 16, v171
	v_and_b32_e32 v201, 0xffff0000, v171
	v_pk_mul_f32 v[170:171], v[166:167], v[166:167]
	v_mov_b32_e32 v154, v135
	v_mov_b32_e32 v179, v198
	v_pk_mul_f32 v[206:207], v[206:207], v[206:207]
	v_lshlrev_b32_e32 v176, 16, v177
	v_and_b32_e32 v103, 0xffff0000, v177
	v_pk_fma_f32 v[170:171], v[174:175], v[174:175], v[170:171]
	v_pk_mul_f32 v[202:203], v[154:155], v[154:155]
	v_mov_b32_e32 v138, v147
	v_pk_fma_f32 v[206:207], v[178:179], v[178:179], v[206:207]
	v_mov_b32_e32 v177, v200
	v_pk_fma_f32 v[170:171], v[172:173], v[172:173], v[170:171]
	v_mov_b32_e32 v168, v153
	v_pk_fma_f32 v[202:203], v[160:161], v[160:161], v[202:203]
	v_pk_mul_f32 v[204:205], v[138:139], v[138:139]
	v_mov_b32_e32 v208, v103
	v_mov_b32_e32 v209, v201
	v_pk_fma_f32 v[206:207], v[176:177], v[176:177], v[206:207]
	v_pk_fma_f32 v[170:171], v[168:169], v[168:169], v[170:171]
	v_pk_fma_f32 v[202:203], v[158:159], v[158:159], v[202:203]
	v_mov_b32_e32 v156, v137
	v_pk_fma_f32 v[204:205], v[144:145], v[144:145], v[204:205]
	v_pk_fma_f32 v[206:207], v[208:209], v[208:209], v[206:207]
	v_pk_fma_f32 v[202:203], v[156:157], v[156:157], v[202:203]
	v_pk_fma_f32 v[204:205], v[142:143], v[142:143], v[204:205]
	v_mov_b32_e32 v140, v149
	v_pk_add_f32 v[170:171], v[206:207], v[170:171]
	v_pk_fma_f32 v[204:205], v[140:141], v[140:141], v[204:205]
	v_pk_add_f32 v[170:171], v[170:171], v[202:203]
	v_mov_b32_e32 v202, v196
	v_pk_add_f32 v[170:171], v[170:171], v[204:205]
	v_mov_b32_e32 v203, v194
	v_pk_add_f32 v[170:171], v[170:171], v[202:203]
	v_mov_b32_e32 v194, v197
	v_pk_add_f32 v[170:171], v[170:171], v[194:195]
	v_mov_b32_e32 v194, v192
	v_mov_b32_e32 v195, v182
	v_pk_add_f32 v[170:171], v[170:171], v[194:195]
	v_mov_b32_e32 v182, v193
	v_pk_add_f32 v[170:171], v[170:171], v[182:183]
	ds_bpermute_b32 v182, v118, v170
	ds_bpermute_b32 v183, v118, v171
	s_waitcnt lgkmcnt(0)
	v_pk_add_f32 v[170:171], v[170:171], v[182:183]
	ds_bpermute_b32 v182, v124, v170
	ds_bpermute_b32 v183, v124, v171
	s_waitcnt lgkmcnt(0)
	v_pk_add_f32 v[170:171], v[170:171], v[182:183]
	s_nop 1
	v_add_f32_dpp v170, v170, v170 row_mirror row_mask:0xf bank_mask:0xf
	v_add_f32_dpp v171, v171, v171 row_mirror row_mask:0xf bank_mask:0xf
	s_nop 1
	v_add_f32_dpp v170, v170, v170 row_half_mirror row_mask:0xf bank_mask:0xf
	v_add_f32_dpp v171, v171, v171 row_half_mirror row_mask:0xf bank_mask:0xf
	s_nop 1
	v_add_f32_dpp v170, v170, v170 quad_perm:[2,3,0,1] row_mask:0xf bank_mask:0xf
	v_add_f32_dpp v171, v171, v171 quad_perm:[2,3,0,1] row_mask:0xf bank_mask:0xf
	s_nop 1
	v_add_f32_dpp v170, v170, v170 quad_perm:[1,0,3,2] row_mask:0xf bank_mask:0xf
	v_add_f32_dpp v171, v171, v171 quad_perm:[1,0,3,2] row_mask:0xf bank_mask:0xf
	s_nop 0
	v_pk_fma_f32 v[170:171], v[170:171], s[34:35], v[188:189] op_sel_hi:[1,0,0]
	s_nop 0
	v_mul_f32_e32 v90, 0x4b800000, v170
	v_cmp_gt_f32_e64 s[10:11], s80, v170
	v_mul_f32_e32 v92, 0x4b800000, v171
	v_cmp_gt_f32_e64 s[12:13], s80, v171
	v_cndmask_b32_e64 v90, v170, v90, s[10:11]
	v_rsq_f32_e32 v90, v90
	v_cndmask_b32_e64 v92, v171, v92, s[12:13]
	v_rsq_f32_e32 v92, v92
	v_mul_f32_e32 v105, 0x45800000, v90
	v_cndmask_b32_e64 v90, v90, v105, s[10:11]
	v_mul_f32_e32 v105, 0x45800000, v92
	v_cndmask_b32_e64 v170, v92, v105, s[12:13]
	v_pk_mul_f32 v[182:183], v[170:171], v[198:199] op_sel_hi:[0,1]
	s_waitcnt vmcnt(0)
	v_pk_fma_f32 v[56:57], v[210:211], v[182:183], v[56:57]
	v_pk_mul_f32 v[182:183], v[170:171], v[200:201] op_sel_hi:[0,1]
	v_pk_fma_f32 v[58:59], v[212:213], v[182:183], v[58:59]
	global_store_dwordx4 v[84:85], v[56:59], off nt
	s_and_saveexec_b64 s[4:5], vcc
	s_cbranch_execz .LBB0_17
	v_mov_b32_e32 v177, v103
	v_mov_b32_e32 v179, v101
	v_pk_mul_f32 v[56:57], v[90:91], v[178:179] op_sel_hi:[0,1]
	v_pk_mul_f32 v[58:59], v[90:91], v[176:177] op_sel_hi:[0,1]
	v_pk_fma_f32 v[56:57], v[210:211], v[56:57], v[60:61]
	v_pk_fma_f32 v[58:59], v[212:213], v[58:59], v[62:63]
	global_store_dwordx4 v[82:83], v[56:59], off nt

.LBB0_132:
	v_add_co_u32_e32 v12, vcc, 0x8000000, v100
	v_add_u32_e32 v0, s55, v132
	s_nop 0
	v_addc_co_u32_e32 v13, vcc, 0, v101, vcc
	v_cmp_gt_i32_e64 s[10:11], s76, v0
	global_load_dwordx2 v[32:33], v[12:13], off offset:512 nt
	global_load_dwordx2 v[38:39], v[12:13], off offset:1024 nt
	global_load_dwordx2 v[108:109], v[12:13], off offset:1536 nt
	v_cndmask_b32_e64 v16, v132, v0, s[10:11]
	global_load_dwordx2 v[110:111], v[12:13], off offset:2048 nt
	v_ashrrev_i32_e32 v17, 31, v16
	v_lshlrev_b64 v[106:107], 12, v[16:17]
	v_lshl_add_u64 v[44:45], v[76:77], 0, v[106:107]
	global_load_dwordx2 v[112:113], v[44:45], off offset:512 nt
	global_load_dwordx2 v[114:115], v[44:45], off offset:1024 nt
	global_load_dwordx2 v[116:117], v[44:45], off offset:1536 nt
	global_load_dwordx2 v[118:119], v[44:45], off offset:2048 nt
	global_load_dwordx2 v[122:123], v[12:13], off offset:2560 nt
	global_load_dwordx2 v[124:125], v[44:45], off offset:2560 nt
	global_load_dwordx2 v[14:15], v[12:13], off nt
	global_load_dwordx2 v[120:121], v[44:45], off nt
	v_lshl_add_u64 v[18:19], v[104:105], 0, v[186:187]
	global_load_dwordx4 v[4:7], v[18:19], off nt
	global_load_dwordx4 v[0:3], v[18:19], off offset:1024 nt
	global_load_dwordx4 v[8:11], v[18:19], off offset:2048 nt
	global_load_dwordx4 v[20:23], v[18:19], off offset:3072 nt
	global_load_dwordx2 v[128:129], v[12:13], off offset:3072 nt
	v_add_co_u32_e32 v18, vcc, s29, v18
	s_waitcnt vmcnt(16)
	v_lshlrev_b32_e32 v198, 16, v32
	v_addc_co_u32_e32 v19, vcc, 0, v19, vcc
	global_load_dwordx2 v[136:137], v[44:45], off offset:3072 nt
	global_load_dwordx4 v[28:31], v[18:19], off nt
	global_load_dwordx4 v[40:43], v[18:19], off offset:1024 nt
	global_load_dwordx2 v[138:139], v[12:13], off offset:3584 nt
	global_load_dwordx4 v[48:51], v[18:19], off offset:2048 nt
	global_load_dwordx4 v[56:59], v[18:19], off offset:3072 nt
	v_lshlrev_b64 v[12:13], 13, v[16:17]
	v_lshl_add_u64 v[46:47], v[96:97], 0, v[12:13]
	v_add_co_u32_e32 v60, vcc, s29, v46
	global_load_dwordx4 v[16:19], v[46:47], off nt
	global_load_dwordx4 v[24:27], v[46:47], off offset:1024 nt
	global_load_dwordx4 v[68:71], v[46:47], off offset:2048 nt
	global_load_dwordx4 v[34:37], v[46:47], off offset:3072 nt
	v_addc_co_u32_e32 v61, vcc, 0, v47, vcc
	global_load_dwordx2 v[210:211], v[44:45], off offset:3584 nt
	s_nop 0
	global_load_dwordx4 v[44:47], v[60:61], off nt
	global_load_dwordx4 v[52:55], v[60:61], off offset:1024 nt
	global_load_dwordx4 v[64:67], v[60:61], off offset:2048 nt
	s_nop 0
	global_load_dwordx4 v[60:63], v[60:61], off offset:3072 nt
	s_waitcnt vmcnt(28)
	v_and_b32_e32 v141, 0xffff0000, v110
	s_waitcnt vmcnt(23)
	v_lshlrev_b32_e32 v140, 16, v122
	v_and_b32_e32 v143, 0xffff0000, v122
	v_mov_b32_e32 v142, v141
	v_and_b32_e32 v203, 0xffff0000, v32
	v_lshlrev_b32_e32 v32, 16, v108
	v_and_b32_e32 v167, 0xffff0000, v108
	v_lshlrev_b32_e32 v164, 16, v109
	v_and_b32_e32 v169, 0xffff0000, v109
	v_lshlrev_b32_e32 v152, 16, v110
	v_lshlrev_b32_e32 v144, 16, v123
	v_mov_b32_e32 v153, v140
	v_pk_mul_f32 v[108:109], v[142:143], v[142:143]
	v_lshlrev_b32_e32 v154, 16, v111
	v_and_b32_e32 v145, 0xffff0000, v111
	v_pk_fma_f32 v[108:109], v[152:153], v[152:153], v[108:109]
	v_mov_b32_e32 v155, v144
	v_and_b32_e32 v159, 0xffff0000, v118
	v_and_b32_e32 v147, 0xffff0000, v123
	v_pk_fma_f32 v[108:109], v[154:155], v[154:155], v[108:109]
	v_mov_b32_e32 v146, v145
	v_pk_fma_f32 v[122:123], v[146:147], v[146:147], v[108:109]
	s_waitcnt vmcnt(22)
	v_lshlrev_b32_e32 v146, 16, v124
	v_and_b32_e32 v149, 0xffff0000, v124
	v_mov_b32_e32 v148, v159
	v_lshlrev_b32_e32 v156, 16, v118
	v_lshlrev_b32_e32 v142, 16, v125
	v_mov_b32_e32 v157, v146
	v_pk_mul_f32 v[108:109], v[148:149], v[148:149]
	v_lshlrev_b32_e32 v178, 16, v38
	v_and_b32_e32 v183, 0xffff0000, v38
	v_lshlrev_b32_e32 v180, 16, v39
	v_and_b32_e32 v193, 0xffff0000, v39
	v_lshlrev_b32_e32 v38, 16, v119
	v_and_b32_e32 v161, 0xffff0000, v119
	v_pk_fma_f32 v[108:109], v[156:157], v[156:157], v[108:109]
	v_mov_b32_e32 v39, v142
	v_and_b32_e32 v151, 0xffff0000, v125
	v_pk_fma_f32 v[108:109], v[38:39], v[38:39], v[108:109]
	v_mov_b32_e32 v150, v161
	s_waitcnt vmcnt(15)
	v_and_b32_e32 v111, 0xffff0000, v128
	v_pk_fma_f32 v[214:215], v[150:151], v[150:151], v[108:109]
	v_mov_b32_e32 v108, v111
	v_lshlrev_b32_e32 v206, 16, v112
	v_and_b32_e32 v179, 0xffff0000, v112
	v_lshlrev_b32_e32 v170, 16, v116
	v_and_b32_e32 v173, 0xffff0000, v116
	v_lshlrev_b32_e32 v162, 16, v117
	v_and_b32_e32 v175, 0xffff0000, v117
	v_lshlrev_b32_e32 v126, 16, v128
	v_lshlrev_b32_e32 v196, 16, v113
	v_and_b32_e32 v181, 0xffff0000, v113
	v_lshlrev_b32_e32 v128, 16, v129
	v_and_b32_e32 v113, 0xffff0000, v129
	v_lshlrev_b32_e32 v200, 16, v33
	v_and_b32_e32 v205, 0xffff0000, v33
	v_lshlrev_b32_e32 v194, 16, v114
	v_and_b32_e32 v33, 0xffff0000, v114
	v_lshlrev_b32_e32 v176, 16, v115
	v_and_b32_e32 v165, 0xffff0000, v115
	v_mov_b32_e32 v114, v113
	v_and_b32_e32 v221, 0xffff0000, v120
	v_and_b32_e32 v239, 0xffff0000, v14
	v_lshlrev_b32_e32 v220, 16, v120
	v_lshlrev_b32_e32 v238, 16, v14
	v_mov_b32_e32 v202, v179
	s_waitcnt vmcnt(14)
	v_lshlrev_b32_e32 v130, 16, v136
	v_and_b32_e32 v133, 0xffff0000, v136
	v_lshlrev_b32_e32 v124, 16, v137
	s_waitcnt vmcnt(11)
	v_lshlrev_b32_e32 v110, 16, v138
	v_and_b32_e32 v109, 0xffff0000, v138
	v_lshlrev_b32_e32 v112, 16, v139
	v_mov_b32_e32 v127, v110
	v_pk_mul_f32 v[116:117], v[108:109], v[108:109]
	v_mov_b32_e32 v129, v112
	v_pk_fma_f32 v[116:117], v[126:127], v[126:127], v[116:117]
	v_and_b32_e32 v115, 0xffff0000, v139
	v_pk_fma_f32 v[116:117], v[128:129], v[128:129], v[116:117]
	v_and_b32_e32 v135, 0xffff0000, v137
	v_pk_fma_f32 v[136:137], v[114:115], v[114:115], v[116:117]
	s_waitcnt vmcnt(4)
	v_lshlrev_b32_e32 v114, 16, v210
	v_and_b32_e32 v117, 0xffff0000, v210
	v_lshlrev_b32_e32 v108, 16, v211
	v_and_b32_e32 v119, 0xffff0000, v211
	ds_read_b128 v[210:213], v209
	v_mov_b32_e32 v250, v221
	v_mov_b32_e32 v251, v239
	v_lshlrev_b32_e32 v216, 16, v121
	v_lshlrev_b32_e32 v218, 16, v15
	v_and_b32_e32 v219, 0xffff0000, v15
	v_mov_b32_e32 v207, v198
	v_pk_mul_f32 v[14:15], v[202:203], v[202:203]
	v_mov_b32_e32 v182, v33
	v_mov_b32_e32 v248, v220
	v_mov_b32_e32 v249, v238
	v_pk_mul_f32 v[250:251], v[250:251], v[250:251]
	v_and_b32_e32 v217, 0xffff0000, v121
	v_pk_fma_f32 v[14:15], v[206:207], v[206:207], v[14:15]
	v_mov_b32_e32 v197, v200
	v_mov_b32_e32 v195, v178
	v_pk_mul_f32 v[120:121], v[182:183], v[182:183]
	v_mov_b32_e32 v166, v173
	v_mov_b32_e32 v244, v216
	v_mov_b32_e32 v245, v218
	v_pk_fma_f32 v[248:249], v[248:249], v[248:249], v[250:251]
	v_pk_fma_f32 v[14:15], v[196:197], v[196:197], v[14:15]
	v_mov_b32_e32 v204, v181
	v_pk_fma_f32 v[120:121], v[194:195], v[194:195], v[120:121]
	v_mov_b32_e32 v177, v180
	v_mov_b32_e32 v171, v32
	v_pk_mul_f32 v[240:241], v[166:167], v[166:167]
	v_mov_b32_e32 v246, v217
	v_mov_b32_e32 v247, v219
	v_pk_fma_f32 v[244:245], v[244:245], v[244:245], v[248:249]
	v_mov_b32_e32 v116, v133
	v_pk_fma_f32 v[14:15], v[204:205], v[204:205], v[14:15]
	v_pk_fma_f32 v[120:121], v[176:177], v[176:177], v[120:121]
	v_mov_b32_e32 v192, v165
	v_pk_fma_f32 v[240:241], v[170:171], v[170:171], v[240:241]
	v_mov_b32_e32 v163, v164
	v_pk_fma_f32 v[244:245], v[246:247], v[246:247], v[244:245]
	v_mov_b32_e32 v131, v114
	v_pk_mul_f32 v[138:139], v[116:117], v[116:117]
	v_pk_fma_f32 v[120:121], v[192:193], v[192:193], v[120:121]
	v_pk_fma_f32 v[240:241], v[162:163], v[162:163], v[240:241]
	v_mov_b32_e32 v168, v175
	v_pk_add_f32 v[14:15], v[244:245], v[14:15]
	v_pk_fma_f32 v[138:139], v[130:131], v[130:131], v[138:139]
	v_mov_b32_e32 v125, v108
	v_pk_fma_f32 v[240:241], v[168:169], v[168:169], v[240:241]
	v_pk_add_f32 v[14:15], v[14:15], v[120:121]
	v_pk_fma_f32 v[138:139], v[124:125], v[124:125], v[138:139]
	v_mov_b32_e32 v118, v135
	v_pk_add_f32 v[14:15], v[14:15], v[240:241]
	v_mov_b32_e32 v120, v214
	v_mov_b32_e32 v121, v122
	v_pk_fma_f32 v[138:139], v[118:119], v[118:119], v[138:139]
	v_pk_add_f32 v[14:15], v[14:15], v[120:121]
	v_mov_b32_e32 v122, v215
	v_pk_add_f32 v[14:15], v[14:15], v[122:123]
	v_mov_b32_e32 v120, v138
	v_mov_b32_e32 v121, v136
	v_pk_add_f32 v[14:15], v[14:15], v[120:121]
	v_mov_b32_e32 v136, v139
	v_pk_add_f32 v[14:15], v[14:15], v[136:137]
	ds_bpermute_b32 v121, v134, v15
	ds_bpermute_b32 v120, v134, v14
	v_lshl_add_u64 v[122:123], v[102:103], 0, v[186:187]
	s_waitcnt lgkmcnt(0)
	v_pk_add_f32 v[14:15], v[14:15], v[120:121]
	ds_bpermute_b32 v121, v158, v15
	ds_bpermute_b32 v120, v158, v14
	s_waitcnt lgkmcnt(0)
	v_pk_add_f32 v[14:15], v[14:15], v[120:121]
	s_nop 1
	v_add_f32_dpp v14, v14, v14 row_mirror row_mask:0xf bank_mask:0xf
	v_add_f32_dpp v15, v15, v15 row_mirror row_mask:0xf bank_mask:0xf
	s_nop 1
	v_add_f32_dpp v14, v14, v14 row_half_mirror row_mask:0xf bank_mask:0xf
	v_add_f32_dpp v15, v15, v15 row_half_mirror row_mask:0xf bank_mask:0xf
	s_nop 1
	v_add_f32_dpp v14, v14, v14 quad_perm:[2,3,0,1] row_mask:0xf bank_mask:0xf
	v_add_f32_dpp v15, v15, v15 quad_perm:[2,3,0,1] row_mask:0xf bank_mask:0xf
	s_nop 1
	v_add_f32_dpp v14, v14, v14 quad_perm:[1,0,3,2] row_mask:0xf bank_mask:0xf
	v_add_f32_dpp v15, v15, v15 quad_perm:[1,0,3,2] row_mask:0xf bank_mask:0xf
	s_nop 0
	v_pk_fma_f32 v[14:15], v[14:15], s[34:35], v[188:189] op_sel_hi:[1,0,0]
	v_lshl_add_u64 v[120:121], v[98:99], 0, v[12:13]
	v_mul_f32_e32 v39, 0x4b800000, v15
	v_cmp_gt_f32_e32 vcc, s80, v15
	s_nop 1
	v_cndmask_b32_e32 v15, v15, v39, vcc
	v_rsq_f32_e32 v15, v15
	s_nop 0
	v_mul_f32_e32 v12, 0x45800000, v15
	v_cndmask_b32_e32 v138, v15, v12, vcc
	v_mul_f32_e32 v15, 0x4b800000, v14
	v_cmp_gt_f32_e32 vcc, s80, v14
	v_pk_mul_f32 v[12:13], v[138:139], v[238:239] op_sel_hi:[0,1]
	s_waitcnt vmcnt(0) lgkmcnt(0)
	v_pk_fma_f32 v[12:13], v[210:211], v[12:13], v[4:5]
	v_cndmask_b32_e32 v14, v14, v15, vcc
	v_rsq_f32_e32 v39, v14
	v_pk_mul_f32 v[14:15], v[138:139], v[218:219] op_sel_hi:[0,1]
	v_pk_fma_f32 v[14:15], v[212:213], v[14:15], v[6:7]
	global_store_dwordx4 v[122:123], v[12:15], off
	v_mul_f32_e32 v4, 0x45800000, v39
	v_cndmask_b32_e32 v136, v39, v4, vcc
	v_pk_mul_f32 v[4:5], v[136:137], v[220:221] op_sel_hi:[0,1]
	v_pk_mul_f32 v[6:7], v[136:137], v[216:217] op_sel_hi:[0,1]
	v_pk_fma_f32 v[4:5], v[210:211], v[4:5], v[16:17]
	v_pk_fma_f32 v[6:7], v[212:213], v[6:7], v[18:19]
	s_and_saveexec_b64 s[4:5], s[10:11]
	s_cbranch_execz .LBB0_134
	global_store_dwordx4 v[120:121], v[4:7], off

.LBB0_148:
	s_or_b64 exec, exec, s[4:5]
	v_mov_b32_e32 v62, v5
	v_mov_b32_e32 v63, v13
	v_mov_b32_e32 v60, v4
	v_mov_b32_e32 v61, v12
	v_pk_mul_f32 v[62:63], v[62:63], v[62:63]
	v_mov_b32_e32 v68, v1
	v_pk_fma_f32 v[60:61], v[60:61], v[60:61], v[62:63]
	v_mov_b32_e32 v62, v6
	v_mov_b32_e32 v63, v14
	v_pk_fma_f32 v[60:61], v[62:63], v[62:63], v[60:61]
	v_mov_b32_e32 v62, v7
	v_mov_b32_e32 v63, v15
	v_mov_b32_e32 v69, v17
	v_pk_fma_f32 v[60:61], v[62:63], v[62:63], v[60:61]
	v_mov_b32_e32 v62, v0
	v_mov_b32_e32 v63, v16
	v_pk_mul_f32 v[68:69], v[68:69], v[68:69]
	v_pk_mul_f32 v[70:71], v[56:57], v[56:57]
	v_pk_fma_f32 v[62:63], v[62:63], v[62:63], v[68:69]
	v_mov_b32_e32 v68, v2
	v_mov_b32_e32 v69, v18
	v_pk_fma_f32 v[62:63], v[68:69], v[68:69], v[62:63]
	v_mov_b32_e32 v68, v3
	v_mov_b32_e32 v69, v19
	v_pk_fma_f32 v[62:63], v[68:69], v[68:69], v[62:63]
	v_mov_b32_e32 v68, v9
	v_mov_b32_e32 v69, v25
	v_pk_add_f32 v[60:61], v[60:61], v[62:63]
	v_mov_b32_e32 v62, v8
	v_mov_b32_e32 v63, v24
	v_pk_mul_f32 v[68:69], v[68:69], v[68:69]
	v_mov_b32_e32 v108, v70
	v_pk_fma_f32 v[62:63], v[62:63], v[62:63], v[68:69]
	v_mov_b32_e32 v68, v10
	v_mov_b32_e32 v69, v26
	v_pk_fma_f32 v[62:63], v[68:69], v[68:69], v[62:63]
	v_mov_b32_e32 v68, v11
	v_mov_b32_e32 v69, v27
	v_pk_fma_f32 v[62:63], v[68:69], v[68:69], v[62:63]
	v_mov_b32_e32 v68, v21
	v_mov_b32_e32 v69, v33
	v_pk_add_f32 v[60:61], v[60:61], v[62:63]
	v_mov_b32_e32 v62, v20
	v_mov_b32_e32 v63, v32
	v_pk_mul_f32 v[68:69], v[68:69], v[68:69]
	s_nop 0
	v_pk_fma_f32 v[62:63], v[62:63], v[62:63], v[68:69]
	v_mov_b32_e32 v68, v22
	v_mov_b32_e32 v69, v34
	v_pk_fma_f32 v[62:63], v[68:69], v[68:69], v[62:63]
	v_mov_b32_e32 v68, v23
	v_mov_b32_e32 v69, v35
	v_pk_fma_f32 v[62:63], v[68:69], v[68:69], v[62:63]
	v_mov_b32_e32 v68, v29
	v_mov_b32_e32 v69, v37
	v_pk_add_f32 v[60:61], v[60:61], v[62:63]
	v_mov_b32_e32 v62, v28
	v_mov_b32_e32 v63, v36
	v_pk_mul_f32 v[68:69], v[68:69], v[68:69]
	s_nop 0
	v_pk_fma_f32 v[62:63], v[62:63], v[62:63], v[68:69]
	v_mov_b32_e32 v68, v30
	v_mov_b32_e32 v69, v38
	v_pk_fma_f32 v[62:63], v[68:69], v[68:69], v[62:63]
	v_mov_b32_e32 v68, v31
	v_mov_b32_e32 v69, v39
	v_pk_fma_f32 v[62:63], v[68:69], v[68:69], v[62:63]
	v_mov_b32_e32 v68, v41
	v_mov_b32_e32 v69, v45
	v_pk_add_f32 v[60:61], v[60:61], v[62:63]
	v_mov_b32_e32 v62, v40
	v_mov_b32_e32 v63, v44
	v_pk_mul_f32 v[68:69], v[68:69], v[68:69]
	s_nop 0
	v_pk_fma_f32 v[62:63], v[62:63], v[62:63], v[68:69]
	v_mov_b32_e32 v68, v42
	v_mov_b32_e32 v69, v46
	v_pk_fma_f32 v[62:63], v[68:69], v[68:69], v[62:63]
	v_mov_b32_e32 v68, v43
	v_mov_b32_e32 v69, v47
	v_pk_fma_f32 v[62:63], v[68:69], v[68:69], v[62:63]
	v_mov_b32_e32 v68, v49
	v_mov_b32_e32 v69, v53
	v_pk_add_f32 v[60:61], v[60:61], v[62:63]
	v_mov_b32_e32 v62, v48
	v_mov_b32_e32 v63, v52
	v_pk_mul_f32 v[68:69], v[68:69], v[68:69]
	s_nop 0
	v_pk_fma_f32 v[62:63], v[62:63], v[62:63], v[68:69]
	v_mov_b32_e32 v68, v50
	v_mov_b32_e32 v69, v54
	v_pk_fma_f32 v[62:63], v[68:69], v[68:69], v[62:63]
	v_mov_b32_e32 v68, v51
	v_mov_b32_e32 v69, v55
	v_pk_fma_f32 v[62:63], v[68:69], v[68:69], v[62:63]
	v_pk_mul_f32 v[68:69], v[66:67], v[66:67]
	v_pk_add_f32 v[60:61], v[60:61], v[62:63]
	v_pk_mul_f32 v[62:63], v[64:65], v[64:65]
	s_nop 0
	v_mov_b32_e32 v109, v62
	v_mov_b32_e32 v62, v71
	v_pk_mul_f32 v[70:71], v[58:59], v[58:59]
	v_pk_add_f32 v[62:63], v[108:109], v[62:63]
	v_mov_b32_e32 v108, v70
	v_mov_b32_e32 v109, v68
	v_pk_add_f32 v[62:63], v[62:63], v[108:109]
	v_mov_b32_e32 v68, v71
	v_pk_add_f32 v[62:63], v[68:69], v[62:63]
	v_lshl_add_u64 v[68:69], v[78:79], 0, v[106:107]
	v_pk_add_f32 v[60:61], v[60:61], v[62:63]
	ds_bpermute_b32 v63, v134, v61
	ds_bpermute_b32 v62, v134, v60
	s_waitcnt lgkmcnt(0)
	v_pk_add_f32 v[60:61], v[60:61], v[62:63]
	ds_bpermute_b32 v63, v158, v61
	ds_bpermute_b32 v62, v158, v60
	s_waitcnt lgkmcnt(0)
	v_pk_add_f32 v[60:61], v[60:61], v[62:63]
	s_nop 1
	v_add_f32_dpp v60, v60, v60 row_mirror row_mask:0xf bank_mask:0xf
	v_add_f32_dpp v61, v61, v61 row_mirror row_mask:0xf bank_mask:0xf
	s_nop 1
	v_add_f32_dpp v60, v60, v60 row_half_mirror row_mask:0xf bank_mask:0xf
	v_add_f32_dpp v61, v61, v61 row_half_mirror row_mask:0xf bank_mask:0xf
	s_nop 1
	v_add_f32_dpp v60, v60, v60 quad_perm:[2,3,0,1] row_mask:0xf bank_mask:0xf
	v_add_f32_dpp v61, v61, v61 quad_perm:[2,3,0,1] row_mask:0xf bank_mask:0xf
	s_nop 1
	v_add_f32_dpp v60, v60, v60 quad_perm:[1,0,3,2] row_mask:0xf bank_mask:0xf
	v_add_f32_dpp v61, v61, v61 quad_perm:[1,0,3,2] row_mask:0xf bank_mask:0xf
	s_nop 0
	v_pk_fma_f32 v[60:61], v[60:61], s[34:35], v[188:189] op_sel_hi:[1,0,0]
	s_nop 0
	v_mul_f32_e32 v62, 0x4b800000, v61
	v_cmp_gt_f32_e64 s[12:13], s80, v61
	v_cmp_gt_f32_e32 vcc, s80, v60
	s_nop 0
	v_cndmask_b32_e64 v61, v61, v62, s[12:13]
	v_rsq_f32_e32 v61, v61
	s_nop 0
	v_mul_f32_e32 v62, 0x45800000, v61
	v_cndmask_b32_e64 v108, v61, v62, s[12:13]
	v_mul_f32_e32 v61, 0x4b800000, v60
	v_cndmask_b32_e32 v60, v60, v61, vcc
	v_rsq_f32_e32 v60, v60
	v_pk_mul_f32 v[12:13], v[12:13], v[108:109] op_sel_hi:[1,0]
	v_pk_mul_f32 v[14:15], v[14:15], v[108:109] op_sel_hi:[1,0]
	v_mul_f32_e32 v61, 0x45800000, v60
	v_cndmask_b32_e32 v70, v60, v61, vcc
	ds_read_b128 v[60:63], v209 offset:8192
	s_waitcnt lgkmcnt(0)
	v_pk_mul_f32 v[12:13], v[60:61], v[12:13]
	v_pk_mul_f32 v[14:15], v[62:63], v[14:15]
	v_cvt_pk_bf16_f32 v12, v12, v13
	v_cvt_pk_bf16_f32 v13, v14, v15
	v_add_co_u32_e32 v14, vcc, 0x4000000, v100
	s_nop 1
	v_addc_co_u32_e32 v15, vcc, 0, v101, vcc
	global_store_dwordx2 v[14:15], v[12:13], off
	s_and_saveexec_b64 s[4:5], s[10:11]
	s_cbranch_execz .LBB0_150
	v_pk_mul_f32 v[4:5], v[4:5], v[70:71] op_sel_hi:[1,0]
	v_pk_mul_f32 v[6:7], v[6:7], v[70:71] op_sel_hi:[1,0]
	v_pk_mul_f32 v[4:5], v[60:61], v[4:5]
	v_pk_mul_f32 v[6:7], v[62:63], v[6:7]
	v_cvt_pk_bf16_f32 v4, v4, v5
	v_cvt_pk_bf16_f32 v5, v6, v7
	global_store_dwordx2 v[68:69], v[4:5], off

.LBB0_180:
	s_ashr_i32 s31, s30, 31
	s_lshl_b64 s[4:5], s[30:31], 11
	s_waitcnt vmcnt(1)
	v_lshl_add_u64 v[8:9], s[4:5], 0, v[68:69]
	v_lshlrev_b64 v[72:73], 1, v[8:9]
	v_lshl_add_u64 v[8:9], s[0:1], 0, v[72:73]
	global_load_dwordx4 v[64:67], v[8:9], off nt
	v_lshl_add_u64 v[72:73], s[2:3], 0, v[72:73]
	global_load_dwordx4 v[80:83], v[72:73], off nt
	s_add_i32 s4, s30, s64
	s_cmpk_lt_i32 s4, 0x2000
	s_cselect_b32 s6, s4, s30
	s_ashr_i32 s7, s6, 31
	s_lshl_b64 s[34:35], s[6:7], 11
	v_lshl_add_u64 v[8:9], s[34:35], 0, v[68:69]
	v_lshlrev_b64 v[8:9], 1, v[8:9]
	v_lshl_add_u64 v[10:11], s[0:1], 0, v[8:9]
	global_load_dwordx4 v[60:63], v[10:11], off nt
	s_add_i32 s26, s53, s30
	s_cmpk_lt_i32 s26, 0x2000
	s_cselect_b64 s[28:29], -1, 0
	s_and_b64 s[6:7], s[28:29], exec
	s_cselect_b32 s6, s26, s30
	s_ashr_i32 s7, s6, 31
	v_readlane_b32 s5, v254, 40
	s_lshl_b64 s[36:37], s[6:7], 11
	s_add_i32 s22, s5, s30
	s_cmpk_lt_i32 s22, 0x2000
	s_cselect_b64 s[24:25], -1, 0
	s_and_b64 s[6:7], s[24:25], exec
	s_cselect_b32 s6, s22, s30
	s_ashr_i32 s7, s6, 31
	s_lshl_b64 s[38:39], s[6:7], 11
	s_add_i32 s18, s55, s30
	s_cmpk_lt_i32 s18, 0x2000
	s_cselect_b64 s[20:21], -1, 0
	s_and_b64 s[6:7], s[20:21], exec
	s_cselect_b32 s6, s18, s30
	s_ashr_i32 s7, s6, 31
	v_readlane_b32 s5, v254, 41
	s_lshl_b64 s[40:41], s[6:7], 11
	s_add_i32 s14, s5, s30
	s_cmpk_lt_i32 s14, 0x2000
	s_cselect_b64 s[16:17], -1, 0
	s_and_b64 s[6:7], s[16:17], exec
	v_lshl_add_u64 v[8:9], s[2:3], 0, v[8:9]
	s_cselect_b32 s6, s14, s30
	global_load_dwordx4 v[56:59], v[8:9], off nt
	v_lshl_add_u64 v[8:9], s[36:37], 0, v[68:69]
	s_ashr_i32 s7, s6, 31
	v_readlane_b32 s5, v254, 42
	v_lshlrev_b64 v[8:9], 1, v[8:9]
	s_lshl_b64 s[42:43], s[6:7], 11
	s_add_i32 s10, s5, s30
	v_lshl_add_u64 v[10:11], s[0:1], 0, v[8:9]
	v_lshl_add_u64 v[8:9], s[2:3], 0, v[8:9]
	s_cmpk_lt_i32 s10, 0x2000
	global_load_dwordx4 v[48:51], v[8:9], off nt
	v_lshl_add_u64 v[8:9], s[38:39], 0, v[68:69]
	s_cselect_b64 s[12:13], -1, 0
	v_lshlrev_b64 v[8:9], 1, v[8:9]
	s_and_b64 s[6:7], s[12:13], exec
	global_load_dwordx4 v[52:55], v[10:11], off nt
	v_lshl_add_u64 v[10:11], s[0:1], 0, v[8:9]
	v_lshl_add_u64 v[8:9], s[2:3], 0, v[8:9]
	s_cselect_b32 s6, s10, s30
	global_load_dwordx4 v[40:43], v[8:9], off nt
	v_lshl_add_u64 v[8:9], s[40:41], 0, v[68:69]
	s_ashr_i32 s7, s6, 31
	v_readlane_b32 s5, v254, 43
	v_lshlrev_b64 v[8:9], 1, v[8:9]
	s_lshl_b64 s[44:45], s[6:7], 11
	s_add_i32 s6, s5, s30
	global_load_dwordx4 v[44:47], v[10:11], off nt
	v_lshl_add_u64 v[10:11], s[0:1], 0, v[8:9]
	v_lshl_add_u64 v[8:9], s[2:3], 0, v[8:9]
	s_cmpk_lt_i32 s6, 0x2000
	global_load_dwordx4 v[32:35], v[8:9], off nt
	v_lshl_add_u64 v[8:9], s[42:43], 0, v[68:69]
	s_cselect_b64 s[8:9], -1, 0
	v_lshlrev_b64 v[8:9], 1, v[8:9]
	s_and_b64 s[46:47], s[8:9], exec
	global_load_dwordx4 v[36:39], v[10:11], off nt
	v_lshl_add_u64 v[10:11], s[0:1], 0, v[8:9]
	v_lshl_add_u64 v[8:9], s[2:3], 0, v[8:9]
	s_cselect_b32 s46, s6, s30
	s_waitcnt vmcnt(9)
	v_lshlrev_b32_e32 v84, 16, v64
	v_and_b32_e32 v85, 0xffff0000, v64
	v_pk_mul_f32 v[86:87], v[84:85], v[84:85]
	v_lshlrev_b32_e32 v64, 16, v65
	v_and_b32_e32 v65, 0xffff0000, v65
	v_pk_mul_f32 v[88:89], v[64:65], v[64:65]
	s_waitcnt vmcnt(8)
	v_lshlrev_b32_e32 v90, 16, v81
	v_and_b32_e32 v91, 0xffff0000, v81
	v_add_f32_e32 v81, v86, v87
	v_lshlrev_b32_e32 v92, 16, v66
	v_and_b32_e32 v93, 0xffff0000, v66
	v_add_f32_e32 v81, v88, v81
	v_pk_mul_f32 v[94:95], v[92:93], v[92:93]
	v_add_f32_e32 v81, v89, v81
	v_lshlrev_b32_e32 v66, 16, v67
	v_and_b32_e32 v67, 0xffff0000, v67
	v_add_f32_e32 v81, v94, v81
	v_pk_mul_f32 v[98:99], v[66:67], v[66:67]
	v_add_f32_e32 v81, v95, v81
	v_add_f32_e32 v81, v98, v81
	v_add_f32_e32 v81, v99, v81
	ds_bpermute_b32 v86, v74, v81
	global_load_dwordx4 v[24:27], v[8:9], off nt
	v_lshl_add_u64 v[8:9], s[44:45], 0, v[68:69]
	s_ashr_i32 s47, s46, 31
	v_lshlrev_b64 v[8:9], 1, v[8:9]
	s_waitcnt lgkmcnt(0)
	v_add_f32_e32 v81, v81, v86
	ds_bpermute_b32 v86, v75, v81
	s_lshl_b64 s[46:47], s[46:47], 11
	global_load_dwordx4 v[28:31], v[10:11], off nt
	v_lshl_add_u64 v[10:11], s[0:1], 0, v[8:9]
	v_lshl_add_u64 v[8:9], s[2:3], 0, v[8:9]
	s_waitcnt lgkmcnt(0)
	v_add_f32_e32 v81, v81, v86
	global_load_dwordx4 v[16:19], v[8:9], off nt
	v_lshl_add_u64 v[8:9], s[46:47], 0, v[68:69]
	v_lshlrev_b64 v[8:9], 1, v[8:9]
	global_load_dwordx4 v[20:23], v[10:11], off nt
	v_lshl_add_u64 v[10:11], s[0:1], 0, v[8:9]
	v_lshl_add_u64 v[8:9], s[2:3], 0, v[8:9]
	s_nop 1
	v_add_f32_dpp v81, v81, v81 row_mirror row_mask:0xf bank_mask:0xf
	global_load_dwordx4 v[12:15], v[10:11], off nt
	global_load_dwordx4 v[8:11], v[8:9], off nt
	v_lshlrev_b32_e32 v96, 16, v82
	v_and_b32_e32 v97, 0xffff0000, v82
	v_lshlrev_b32_e32 v82, 16, v83
	s_nop 1
	v_add_f32_dpp v81, v81, v81 row_half_mirror row_mask:0xf bank_mask:0xf
	v_and_b32_e32 v83, 0xffff0000, v83
	s_lshl_b64 s[30:31], s[30:31], 12
	v_lshl_add_u64 v[72:73], v[70:71], 0, s[30:31]
	s_cmpk_gt_i32 s4, 0x1fff
	s_nop 1
	v_add_f32_dpp v81, v81, v81 quad_perm:[2,3,0,1] row_mask:0xf bank_mask:0xf
	s_nop 1
	v_add_f32_dpp v81, v81, v81 quad_perm:[1,0,3,2] row_mask:0xf bank_mask:0xf
	v_fmamk_f32 v81, v81, 0x3b000000, v188
	v_cmp_gt_f32_e32 vcc, s80, v81
	v_mul_f32_e32 v86, 0x4b800000, v81
	s_nop 0
	v_cndmask_b32_e32 v81, v81, v86, vcc
	v_rsq_f32_e32 v81, v81
	s_nop 0
	v_mul_f32_e32 v86, 0x45800000, v81
	v_cndmask_b32_e32 v86, v81, v86, vcc
	v_pk_mul_f32 v[66:67], v[86:87], v[66:67] op_sel_hi:[0,1]
	v_pk_mul_f32 v[66:67], v[2:3], v[66:67]
	v_pk_mul_f32 v[64:65], v[86:87], v[64:65] op_sel_hi:[0,1]
	v_pk_mul_f32 v[66:67], v[66:67], v[82:83]
	v_pk_mul_f32 v[82:83], v[86:87], v[92:93] op_sel_hi:[0,1]
	v_pk_mul_f32 v[82:83], v[0:1], v[82:83]
	v_cvt_pk_bf16_f32 v67, v66, v67
	v_pk_mul_f32 v[82:83], v[82:83], v[96:97]
	v_pk_mul_f32 v[64:65], v[6:7], v[64:65]
	v_cvt_pk_bf16_f32 v66, v82, v83
	v_pk_mul_f32 v[82:83], v[86:87], v[84:85] op_sel_hi:[0,1]
	v_pk_mul_f32 v[82:83], v[4:5], v[82:83]
	v_lshlrev_b32_e32 v84, 16, v80
	v_and_b32_e32 v85, 0xffff0000, v80
	v_pk_mul_f32 v[64:65], v[64:65], v[90:91]
	v_pk_mul_f32 v[80:81], v[82:83], v[84:85]
	v_cvt_pk_bf16_f32 v65, v64, v65
	v_cvt_pk_bf16_f32 v64, v80, v81
	global_store_dwordx4 v[72:73], v[64:67], off
	s_waitcnt vmcnt(14)
	s_nop 0
	v_lshlrev_b32_e32 v64, 16, v60
	v_and_b32_e32 v65, 0xffff0000, v60
	v_lshlrev_b32_e32 v60, 16, v61
	v_and_b32_e32 v61, 0xffff0000, v61
	v_pk_mul_f32 v[72:73], v[64:65], v[64:65]
	v_pk_mul_f32 v[80:81], v[60:61], v[60:61]
	v_add_f32_e32 v72, v72, v73
	v_lshlrev_b32_e32 v66, 16, v62
	v_and_b32_e32 v67, 0xffff0000, v62
	v_add_f32_e32 v72, v80, v72
	v_pk_mul_f32 v[82:83], v[66:67], v[66:67]
	v_add_f32_e32 v72, v81, v72
	v_lshlrev_b32_e32 v62, 16, v63
	v_and_b32_e32 v63, 0xffff0000, v63
	v_add_f32_e32 v72, v82, v72
	v_pk_mul_f32 v[84:85], v[62:63], v[62:63]
	v_add_f32_e32 v72, v83, v72
	v_add_f32_e32 v72, v84, v72
	v_add_f32_e32 v72, v85, v72
	ds_bpermute_b32 v73, v74, v72
	s_waitcnt lgkmcnt(0)
	v_add_f32_e32 v72, v72, v73
	ds_bpermute_b32 v73, v75, v72
	s_waitcnt lgkmcnt(0)
	v_add_f32_e32 v72, v72, v73
	s_nop 1
	v_add_f32_dpp v72, v72, v72 row_mirror row_mask:0xf bank_mask:0xf
	s_nop 1
	v_add_f32_dpp v72, v72, v72 row_half_mirror row_mask:0xf bank_mask:0xf
	s_nop 1
	v_add_f32_dpp v72, v72, v72 quad_perm:[2,3,0,1] row_mask:0xf bank_mask:0xf
	ds_bpermute_b32 v73, v79, v72
	s_cbranch_scc1 .LBB0_182
	s_waitcnt lgkmcnt(0)
	v_add_f32_e32 v72, v72, v73
	v_fmamk_f32 v72, v72, 0x3b000000, v188
	v_cmp_gt_f32_e32 vcc, s80, v72
	v_mul_f32_e32 v73, 0x4b800000, v72
	s_waitcnt vmcnt(13)
	v_lshlrev_b32_e32 v82, 16, v59
	v_cndmask_b32_e32 v72, v72, v73, vcc
	v_rsq_f32_e32 v72, v72
	v_and_b32_e32 v83, 0xffff0000, v59
	s_ashr_i32 s5, s4, 31
	s_lshl_b64 s[30:31], s[4:5], 12
	v_mul_f32_e32 v73, 0x45800000, v72
	v_cndmask_b32_e32 v72, v72, v73, vcc
	v_pk_mul_f32 v[62:63], v[72:73], v[62:63] op_sel_hi:[0,1]
	v_pk_mul_f32 v[62:63], v[2:3], v[62:63]
	v_pk_mul_f32 v[60:61], v[72:73], v[60:61] op_sel_hi:[0,1]
	v_pk_mul_f32 v[62:63], v[62:63], v[82:83]
	v_pk_mul_f32 v[60:61], v[6:7], v[60:61]
	v_cvt_pk_bf16_f32 v59, v62, v63
	v_pk_mul_f32 v[62:63], v[72:73], v[66:67] op_sel_hi:[0,1]
	v_pk_mul_f32 v[62:63], v[0:1], v[62:63]
	v_lshlrev_b32_e32 v66, 16, v58
	v_and_b32_e32 v67, 0xffff0000, v58
	v_pk_mul_f32 v[62:63], v[62:63], v[66:67]
	v_lshl_add_u64 v[80:81], v[70:71], 0, s[30:31]
	v_cvt_pk_bf16_f32 v58, v62, v63
	v_lshlrev_b32_e32 v62, 16, v57
	v_and_b32_e32 v63, 0xffff0000, v57
	v_pk_mul_f32 v[60:61], v[60:61], v[62:63]
	v_lshlrev_b32_e32 v62, 16, v56
	v_cvt_pk_bf16_f32 v57, v60, v61
	v_pk_mul_f32 v[60:61], v[72:73], v[64:65] op_sel_hi:[0,1]
	v_pk_mul_f32 v[60:61], v[4:5], v[60:61]
	v_and_b32_e32 v63, 0xffff0000, v56
	v_pk_mul_f32 v[60:61], v[60:61], v[62:63]
	s_nop 0
	v_cvt_pk_bf16_f32 v56, v60, v61
	global_store_dwordx4 v[80:81], v[56:59], off
.LBB0_182:
	s_waitcnt vmcnt(11)
	s_nop 0
	v_lshlrev_b32_e32 v56, 16, v52
	v_and_b32_e32 v57, 0xffff0000, v52
	v_lshlrev_b32_e32 v52, 16, v53
	v_and_b32_e32 v53, 0xffff0000, v53
	v_pk_mul_f32 v[60:61], v[56:57], v[56:57]
	v_pk_mul_f32 v[62:63], v[52:53], v[52:53]
	v_add_f32_e32 v60, v60, v61
	v_lshlrev_b32_e32 v58, 16, v54
	v_and_b32_e32 v59, 0xffff0000, v54
	v_add_f32_e32 v60, v62, v60
	v_pk_mul_f32 v[64:65], v[58:59], v[58:59]
	v_add_f32_e32 v60, v63, v60
	v_lshlrev_b32_e32 v54, 16, v55
	v_and_b32_e32 v55, 0xffff0000, v55
	v_add_f32_e32 v60, v64, v60
	v_pk_mul_f32 v[66:67], v[54:55], v[54:55]
	v_add_f32_e32 v60, v65, v60
	v_add_f32_e32 v60, v66, v60
	v_add_f32_e32 v60, v67, v60
	ds_bpermute_b32 v61, v74, v60
	s_andn2_b64 vcc, exec, s[28:29]
	s_waitcnt lgkmcnt(0)
	v_add_f32_e32 v60, v60, v61
	ds_bpermute_b32 v61, v75, v60
	s_waitcnt lgkmcnt(0)
	v_add_f32_e32 v60, v60, v61
	s_nop 1
	v_add_f32_dpp v60, v60, v60 row_mirror row_mask:0xf bank_mask:0xf
	s_nop 1
	v_add_f32_dpp v60, v60, v60 row_half_mirror row_mask:0xf bank_mask:0xf
	s_nop 1
	v_add_f32_dpp v60, v60, v60 quad_perm:[2,3,0,1] row_mask:0xf bank_mask:0xf
	ds_bpermute_b32 v61, v79, v60
	s_cbranch_vccnz .LBB0_184
	s_waitcnt lgkmcnt(0)
	v_add_f32_e32 v60, v60, v61
	v_fmamk_f32 v60, v60, 0x3b000000, v188
	v_cmp_gt_f32_e32 vcc, s80, v60
	v_mul_f32_e32 v61, 0x4b800000, v60
	v_lshlrev_b32_e32 v64, 16, v51
	v_cndmask_b32_e32 v60, v60, v61, vcc
	v_rsq_f32_e32 v60, v60
	v_and_b32_e32 v65, 0xffff0000, v51
	s_ashr_i32 s27, s26, 31
	s_lshl_b64 s[26:27], s[26:27], 12
	v_mul_f32_e32 v61, 0x45800000, v60
	v_cndmask_b32_e32 v60, v60, v61, vcc
	v_pk_mul_f32 v[54:55], v[60:61], v[54:55] op_sel_hi:[0,1]
	v_pk_mul_f32 v[54:55], v[2:3], v[54:55]
	v_pk_mul_f32 v[58:59], v[60:61], v[58:59] op_sel_hi:[0,1]
	v_pk_mul_f32 v[54:55], v[54:55], v[64:65]
	v_pk_mul_f32 v[58:59], v[0:1], v[58:59]
	v_cvt_pk_bf16_f32 v51, v54, v55
	v_lshlrev_b32_e32 v54, 16, v50
	v_and_b32_e32 v55, 0xffff0000, v50
	v_pk_mul_f32 v[54:55], v[58:59], v[54:55]
	v_pk_mul_f32 v[52:53], v[60:61], v[52:53] op_sel_hi:[0,1]
	v_cvt_pk_bf16_f32 v50, v54, v55
	v_lshlrev_b32_e32 v54, 16, v49
	v_and_b32_e32 v55, 0xffff0000, v49
	v_pk_mul_f32 v[52:53], v[6:7], v[52:53]
	v_lshl_add_u64 v[62:63], v[70:71], 0, s[26:27]
	v_pk_mul_f32 v[52:53], v[52:53], v[54:55]
	v_pk_mul_f32 v[54:55], v[60:61], v[56:57] op_sel_hi:[0,1]
	v_cvt_pk_bf16_f32 v49, v52, v53
	v_lshlrev_b32_e32 v52, 16, v48
	v_and_b32_e32 v53, 0xffff0000, v48
	v_pk_mul_f32 v[54:55], v[4:5], v[54:55]
	s_nop 0
	v_pk_mul_f32 v[52:53], v[54:55], v[52:53]
	s_nop 0
	v_cvt_pk_bf16_f32 v48, v52, v53
	global_store_dwordx4 v[62:63], v[48:51], off
.LBB0_184:
	s_waitcnt vmcnt(9)
	s_nop 0
	v_lshlrev_b32_e32 v48, 16, v44
	v_and_b32_e32 v49, 0xffff0000, v44
	v_lshlrev_b32_e32 v44, 16, v45
	v_and_b32_e32 v45, 0xffff0000, v45
	v_pk_mul_f32 v[52:53], v[48:49], v[48:49]
	v_pk_mul_f32 v[54:55], v[44:45], v[44:45]
	v_add_f32_e32 v52, v52, v53
	v_lshlrev_b32_e32 v50, 16, v46
	v_and_b32_e32 v51, 0xffff0000, v46
	v_add_f32_e32 v52, v54, v52
	v_pk_mul_f32 v[56:57], v[50:51], v[50:51]
	v_add_f32_e32 v52, v55, v52
	v_lshlrev_b32_e32 v46, 16, v47
	v_and_b32_e32 v47, 0xffff0000, v47
	v_add_f32_e32 v52, v56, v52
	v_pk_mul_f32 v[58:59], v[46:47], v[46:47]
	v_add_f32_e32 v52, v57, v52
	v_add_f32_e32 v52, v58, v52
	v_add_f32_e32 v52, v59, v52
	ds_bpermute_b32 v53, v74, v52
	s_andn2_b64 vcc, exec, s[24:25]
	s_waitcnt lgkmcnt(0)
	v_add_f32_e32 v52, v52, v53
	ds_bpermute_b32 v53, v75, v52
	s_waitcnt lgkmcnt(0)
	v_add_f32_e32 v52, v52, v53
	s_nop 1
	v_add_f32_dpp v52, v52, v52 row_mirror row_mask:0xf bank_mask:0xf
	s_nop 1
	v_add_f32_dpp v52, v52, v52 row_half_mirror row_mask:0xf bank_mask:0xf
	s_nop 1
	v_add_f32_dpp v52, v52, v52 quad_perm:[2,3,0,1] row_mask:0xf bank_mask:0xf
	ds_bpermute_b32 v53, v79, v52
	s_cbranch_vccnz .LBB0_186
	s_waitcnt lgkmcnt(0)
	v_add_f32_e32 v52, v52, v53
	v_fmamk_f32 v52, v52, 0x3b000000, v188
	v_cmp_gt_f32_e32 vcc, s80, v52
	v_mul_f32_e32 v53, 0x4b800000, v52
	v_lshlrev_b32_e32 v56, 16, v43
	v_cndmask_b32_e32 v52, v52, v53, vcc
	v_rsq_f32_e32 v52, v52
	v_and_b32_e32 v57, 0xffff0000, v43
	s_ashr_i32 s23, s22, 31
	s_lshl_b64 s[22:23], s[22:23], 12
	v_mul_f32_e32 v53, 0x45800000, v52
	v_cndmask_b32_e32 v52, v52, v53, vcc
	v_pk_mul_f32 v[46:47], v[52:53], v[46:47] op_sel_hi:[0,1]
	v_pk_mul_f32 v[46:47], v[2:3], v[46:47]
	v_pk_mul_f32 v[50:51], v[52:53], v[50:51] op_sel_hi:[0,1]
	v_pk_mul_f32 v[46:47], v[46:47], v[56:57]
	v_pk_mul_f32 v[50:51], v[0:1], v[50:51]
	v_cvt_pk_bf16_f32 v43, v46, v47
	v_lshlrev_b32_e32 v46, 16, v42
	v_and_b32_e32 v47, 0xffff0000, v42
	v_pk_mul_f32 v[46:47], v[50:51], v[46:47]
	v_pk_mul_f32 v[44:45], v[52:53], v[44:45] op_sel_hi:[0,1]
	v_cvt_pk_bf16_f32 v42, v46, v47
	v_lshlrev_b32_e32 v46, 16, v41
	v_and_b32_e32 v47, 0xffff0000, v41
	v_pk_mul_f32 v[44:45], v[6:7], v[44:45]
	v_lshl_add_u64 v[54:55], v[70:71], 0, s[22:23]
	v_pk_mul_f32 v[44:45], v[44:45], v[46:47]
	v_pk_mul_f32 v[46:47], v[52:53], v[48:49] op_sel_hi:[0,1]
	v_cvt_pk_bf16_f32 v41, v44, v45
	v_lshlrev_b32_e32 v44, 16, v40
	v_and_b32_e32 v45, 0xffff0000, v40
	v_pk_mul_f32 v[46:47], v[4:5], v[46:47]
	s_nop 0
	v_pk_mul_f32 v[44:45], v[46:47], v[44:45]
	s_nop 0
	v_cvt_pk_bf16_f32 v40, v44, v45
	global_store_dwordx4 v[54:55], v[40:43], off
.LBB0_186:
	s_waitcnt vmcnt(7)
	s_nop 0
	v_lshlrev_b32_e32 v40, 16, v36
	v_and_b32_e32 v41, 0xffff0000, v36
	v_lshlrev_b32_e32 v36, 16, v37
	v_and_b32_e32 v37, 0xffff0000, v37
	v_pk_mul_f32 v[44:45], v[40:41], v[40:41]
	v_pk_mul_f32 v[46:47], v[36:37], v[36:37]
	v_add_f32_e32 v44, v44, v45
	v_lshlrev_b32_e32 v42, 16, v38
	v_and_b32_e32 v43, 0xffff0000, v38
	v_add_f32_e32 v44, v46, v44
	v_pk_mul_f32 v[48:49], v[42:43], v[42:43]
	v_add_f32_e32 v44, v47, v44
	v_lshlrev_b32_e32 v38, 16, v39
	v_and_b32_e32 v39, 0xffff0000, v39
	v_add_f32_e32 v44, v48, v44
	v_pk_mul_f32 v[50:51], v[38:39], v[38:39]
	v_add_f32_e32 v44, v49, v44
	v_add_f32_e32 v44, v50, v44
	v_add_f32_e32 v44, v51, v44
	ds_bpermute_b32 v45, v74, v44
	s_andn2_b64 vcc, exec, s[20:21]
	s_waitcnt lgkmcnt(0)
	v_add_f32_e32 v44, v44, v45
	ds_bpermute_b32 v45, v75, v44
	s_waitcnt lgkmcnt(0)
	v_add_f32_e32 v44, v44, v45
	s_nop 1
	v_add_f32_dpp v44, v44, v44 row_mirror row_mask:0xf bank_mask:0xf
	s_nop 1
	v_add_f32_dpp v44, v44, v44 row_half_mirror row_mask:0xf bank_mask:0xf
	s_nop 1
	v_add_f32_dpp v44, v44, v44 quad_perm:[2,3,0,1] row_mask:0xf bank_mask:0xf
	ds_bpermute_b32 v45, v79, v44
	s_cbranch_vccnz .LBB0_188
	s_waitcnt lgkmcnt(0)
	v_add_f32_e32 v44, v44, v45
	v_fmamk_f32 v44, v44, 0x3b000000, v188
	v_cmp_gt_f32_e32 vcc, s80, v44
	v_mul_f32_e32 v45, 0x4b800000, v44
	v_lshlrev_b32_e32 v48, 16, v35
	v_cndmask_b32_e32 v44, v44, v45, vcc
	v_rsq_f32_e32 v44, v44
	v_and_b32_e32 v49, 0xffff0000, v35
	s_ashr_i32 s19, s18, 31
	s_lshl_b64 s[18:19], s[18:19], 12
	v_mul_f32_e32 v45, 0x45800000, v44
	v_cndmask_b32_e32 v44, v44, v45, vcc
	v_pk_mul_f32 v[38:39], v[44:45], v[38:39] op_sel_hi:[0,1]
	v_pk_mul_f32 v[38:39], v[2:3], v[38:39]
	v_pk_mul_f32 v[42:43], v[44:45], v[42:43] op_sel_hi:[0,1]
	v_pk_mul_f32 v[38:39], v[38:39], v[48:49]
	v_pk_mul_f32 v[42:43], v[0:1], v[42:43]
	v_cvt_pk_bf16_f32 v35, v38, v39
	v_lshlrev_b32_e32 v38, 16, v34
	v_and_b32_e32 v39, 0xffff0000, v34
	v_pk_mul_f32 v[38:39], v[42:43], v[38:39]
	v_pk_mul_f32 v[36:37], v[44:45], v[36:37] op_sel_hi:[0,1]
	v_cvt_pk_bf16_f32 v34, v38, v39
	v_lshlrev_b32_e32 v38, 16, v33
	v_and_b32_e32 v39, 0xffff0000, v33
	v_pk_mul_f32 v[36:37], v[6:7], v[36:37]
	v_lshl_add_u64 v[46:47], v[70:71], 0, s[18:19]
	v_pk_mul_f32 v[36:37], v[36:37], v[38:39]
	v_pk_mul_f32 v[38:39], v[44:45], v[40:41] op_sel_hi:[0,1]
	v_cvt_pk_bf16_f32 v33, v36, v37
	v_lshlrev_b32_e32 v36, 16, v32
	v_and_b32_e32 v37, 0xffff0000, v32
	v_pk_mul_f32 v[38:39], v[4:5], v[38:39]
	s_nop 0
	v_pk_mul_f32 v[36:37], v[38:39], v[36:37]
	s_nop 0
	v_cvt_pk_bf16_f32 v32, v36, v37
	global_store_dwordx4 v[46:47], v[32:35], off
.LBB0_188:
	s_waitcnt vmcnt(5)
	s_nop 0
	v_lshlrev_b32_e32 v32, 16, v28
	v_and_b32_e32 v33, 0xffff0000, v28
	v_lshlrev_b32_e32 v28, 16, v29
	v_and_b32_e32 v29, 0xffff0000, v29
	v_pk_mul_f32 v[36:37], v[32:33], v[32:33]
	v_pk_mul_f32 v[38:39], v[28:29], v[28:29]
	v_add_f32_e32 v36, v36, v37
	v_lshlrev_b32_e32 v34, 16, v30
	v_and_b32_e32 v35, 0xffff0000, v30
	v_add_f32_e32 v36, v38, v36
	v_pk_mul_f32 v[40:41], v[34:35], v[34:35]
	v_add_f32_e32 v36, v39, v36
	v_lshlrev_b32_e32 v30, 16, v31
	v_and_b32_e32 v31, 0xffff0000, v31
	v_add_f32_e32 v36, v40, v36
	v_pk_mul_f32 v[42:43], v[30:31], v[30:31]
	v_add_f32_e32 v36, v41, v36
	v_add_f32_e32 v36, v42, v36
	v_add_f32_e32 v36, v43, v36
	ds_bpermute_b32 v37, v74, v36
	s_andn2_b64 vcc, exec, s[16:17]
	s_waitcnt lgkmcnt(0)
	v_add_f32_e32 v36, v36, v37
	ds_bpermute_b32 v37, v75, v36
	s_waitcnt lgkmcnt(0)
	v_add_f32_e32 v36, v36, v37
	s_nop 1
	v_add_f32_dpp v36, v36, v36 row_mirror row_mask:0xf bank_mask:0xf
	s_nop 1
	v_add_f32_dpp v36, v36, v36 row_half_mirror row_mask:0xf bank_mask:0xf
	s_nop 1
	v_add_f32_dpp v36, v36, v36 quad_perm:[2,3,0,1] row_mask:0xf bank_mask:0xf
	ds_bpermute_b32 v37, v79, v36
	s_cbranch_vccnz .LBB0_190
	s_waitcnt lgkmcnt(0)
	v_add_f32_e32 v36, v36, v37
	v_fmamk_f32 v36, v36, 0x3b000000, v188
	v_cmp_gt_f32_e32 vcc, s80, v36
	v_mul_f32_e32 v37, 0x4b800000, v36
	v_lshlrev_b32_e32 v40, 16, v27
	v_cndmask_b32_e32 v36, v36, v37, vcc
	v_rsq_f32_e32 v36, v36
	v_and_b32_e32 v41, 0xffff0000, v27
	s_ashr_i32 s15, s14, 31
	s_lshl_b64 s[14:15], s[14:15], 12
	v_mul_f32_e32 v37, 0x45800000, v36
	v_cndmask_b32_e32 v36, v36, v37, vcc
	v_pk_mul_f32 v[30:31], v[36:37], v[30:31] op_sel_hi:[0,1]
	v_pk_mul_f32 v[30:31], v[2:3], v[30:31]
	v_pk_mul_f32 v[34:35], v[36:37], v[34:35] op_sel_hi:[0,1]
	v_pk_mul_f32 v[30:31], v[30:31], v[40:41]
	v_pk_mul_f32 v[34:35], v[0:1], v[34:35]
	v_cvt_pk_bf16_f32 v27, v30, v31
	v_lshlrev_b32_e32 v30, 16, v26
	v_and_b32_e32 v31, 0xffff0000, v26
	v_pk_mul_f32 v[30:31], v[34:35], v[30:31]
	v_pk_mul_f32 v[28:29], v[36:37], v[28:29] op_sel_hi:[0,1]
	v_cvt_pk_bf16_f32 v26, v30, v31
	v_lshlrev_b32_e32 v30, 16, v25
	v_and_b32_e32 v31, 0xffff0000, v25
	v_pk_mul_f32 v[28:29], v[6:7], v[28:29]
	v_lshl_add_u64 v[38:39], v[70:71], 0, s[14:15]
	v_pk_mul_f32 v[28:29], v[28:29], v[30:31]
	v_pk_mul_f32 v[30:31], v[36:37], v[32:33] op_sel_hi:[0,1]
	v_cvt_pk_bf16_f32 v25, v28, v29
	v_lshlrev_b32_e32 v28, 16, v24
	v_and_b32_e32 v29, 0xffff0000, v24
	v_pk_mul_f32 v[30:31], v[4:5], v[30:31]
	s_nop 0
	v_pk_mul_f32 v[28:29], v[30:31], v[28:29]
	s_nop 0
	v_cvt_pk_bf16_f32 v24, v28, v29
	global_store_dwordx4 v[38:39], v[24:27], off
.LBB0_190:
	s_waitcnt vmcnt(3)
	s_nop 0
	v_lshlrev_b32_e32 v24, 16, v20
	v_and_b32_e32 v25, 0xffff0000, v20
	v_lshlrev_b32_e32 v20, 16, v21
	v_and_b32_e32 v21, 0xffff0000, v21
	v_pk_mul_f32 v[28:29], v[24:25], v[24:25]
	v_pk_mul_f32 v[30:31], v[20:21], v[20:21]
	v_add_f32_e32 v28, v28, v29
	v_lshlrev_b32_e32 v26, 16, v22
	v_and_b32_e32 v27, 0xffff0000, v22
	v_add_f32_e32 v28, v30, v28
	v_pk_mul_f32 v[32:33], v[26:27], v[26:27]
	v_add_f32_e32 v28, v31, v28
	v_lshlrev_b32_e32 v22, 16, v23
	v_and_b32_e32 v23, 0xffff0000, v23
	v_add_f32_e32 v28, v32, v28
	v_pk_mul_f32 v[34:35], v[22:23], v[22:23]
	v_add_f32_e32 v28, v33, v28
	v_add_f32_e32 v28, v34, v28
	v_add_f32_e32 v28, v35, v28
	ds_bpermute_b32 v29, v74, v28
	s_andn2_b64 vcc, exec, s[12:13]
	s_waitcnt lgkmcnt(0)
	v_add_f32_e32 v28, v28, v29
	ds_bpermute_b32 v29, v75, v28
	s_waitcnt lgkmcnt(0)
	v_add_f32_e32 v28, v28, v29
	s_nop 1
	v_add_f32_dpp v28, v28, v28 row_mirror row_mask:0xf bank_mask:0xf
	s_nop 1
	v_add_f32_dpp v28, v28, v28 row_half_mirror row_mask:0xf bank_mask:0xf
	s_nop 1
	v_add_f32_dpp v28, v28, v28 quad_perm:[2,3,0,1] row_mask:0xf bank_mask:0xf
	ds_bpermute_b32 v29, v79, v28
	s_cbranch_vccnz .LBB0_192
	s_waitcnt lgkmcnt(0)
	v_add_f32_e32 v28, v28, v29
	v_fmamk_f32 v28, v28, 0x3b000000, v188
	v_cmp_gt_f32_e32 vcc, s80, v28
	v_mul_f32_e32 v29, 0x4b800000, v28
	v_lshlrev_b32_e32 v32, 16, v19
	v_cndmask_b32_e32 v28, v28, v29, vcc
	v_rsq_f32_e32 v28, v28
	v_and_b32_e32 v33, 0xffff0000, v19
	s_ashr_i32 s11, s10, 31
	s_lshl_b64 s[10:11], s[10:11], 12
	v_mul_f32_e32 v29, 0x45800000, v28
	v_cndmask_b32_e32 v28, v28, v29, vcc
	v_pk_mul_f32 v[22:23], v[28:29], v[22:23] op_sel_hi:[0,1]
	v_pk_mul_f32 v[22:23], v[2:3], v[22:23]
	v_pk_mul_f32 v[26:27], v[28:29], v[26:27] op_sel_hi:[0,1]
	v_pk_mul_f32 v[22:23], v[22:23], v[32:33]
	v_pk_mul_f32 v[26:27], v[0:1], v[26:27]
	v_cvt_pk_bf16_f32 v19, v22, v23
	v_lshlrev_b32_e32 v22, 16, v18
	v_and_b32_e32 v23, 0xffff0000, v18
	v_pk_mul_f32 v[22:23], v[26:27], v[22:23]
	v_pk_mul_f32 v[20:21], v[28:29], v[20:21] op_sel_hi:[0,1]
	v_cvt_pk_bf16_f32 v18, v22, v23
	v_lshlrev_b32_e32 v22, 16, v17
	v_and_b32_e32 v23, 0xffff0000, v17
	v_pk_mul_f32 v[20:21], v[6:7], v[20:21]
	v_lshl_add_u64 v[30:31], v[70:71], 0, s[10:11]
	v_pk_mul_f32 v[20:21], v[20:21], v[22:23]
	v_pk_mul_f32 v[22:23], v[28:29], v[24:25] op_sel_hi:[0,1]
	v_cvt_pk_bf16_f32 v17, v20, v21
	v_lshlrev_b32_e32 v20, 16, v16
	v_and_b32_e32 v21, 0xffff0000, v16
	v_pk_mul_f32 v[22:23], v[4:5], v[22:23]
	s_nop 0
	v_pk_mul_f32 v[20:21], v[22:23], v[20:21]
	s_nop 0
	v_cvt_pk_bf16_f32 v16, v20, v21
	global_store_dwordx4 v[30:31], v[16:19], off
.LBB0_192:
	s_waitcnt vmcnt(2)
	s_nop 0
	v_lshlrev_b32_e32 v16, 16, v12
	v_and_b32_e32 v17, 0xffff0000, v12
	v_lshlrev_b32_e32 v12, 16, v13
	v_and_b32_e32 v13, 0xffff0000, v13
	v_pk_mul_f32 v[20:21], v[16:17], v[16:17]
	v_pk_mul_f32 v[22:23], v[12:13], v[12:13]
	v_add_f32_e32 v20, v20, v21
	v_lshlrev_b32_e32 v18, 16, v14
	v_and_b32_e32 v19, 0xffff0000, v14
	v_add_f32_e32 v20, v22, v20
	v_pk_mul_f32 v[24:25], v[18:19], v[18:19]
	v_add_f32_e32 v20, v23, v20
	v_lshlrev_b32_e32 v14, 16, v15
	v_and_b32_e32 v15, 0xffff0000, v15
	v_add_f32_e32 v20, v24, v20
	v_pk_mul_f32 v[26:27], v[14:15], v[14:15]
	v_add_f32_e32 v20, v25, v20
	v_add_f32_e32 v20, v26, v20
	v_add_f32_e32 v20, v27, v20
	ds_bpermute_b32 v21, v74, v20
	s_andn2_b64 vcc, exec, s[8:9]
	s_waitcnt lgkmcnt(0)
	v_add_f32_e32 v20, v20, v21
	ds_bpermute_b32 v21, v75, v20
	s_waitcnt lgkmcnt(0)
	v_add_f32_e32 v20, v20, v21
	s_nop 1
	v_add_f32_dpp v20, v20, v20 row_mirror row_mask:0xf bank_mask:0xf
	s_nop 1
	v_add_f32_dpp v20, v20, v20 row_half_mirror row_mask:0xf bank_mask:0xf
	s_nop 1
	v_add_f32_dpp v20, v20, v20 quad_perm:[2,3,0,1] row_mask:0xf bank_mask:0xf
	ds_bpermute_b32 v21, v79, v20
	s_cbranch_vccnz .LBB0_179
	s_waitcnt lgkmcnt(0)
	v_add_f32_e32 v20, v20, v21
	v_fmamk_f32 v20, v20, 0x3b000000, v188
	v_cmp_gt_f32_e32 vcc, s80, v20
	v_mul_f32_e32 v21, 0x4b800000, v20
	s_waitcnt vmcnt(1)
	v_lshlrev_b32_e32 v24, 16, v11
	v_cndmask_b32_e32 v20, v20, v21, vcc
	v_rsq_f32_e32 v20, v20
	v_and_b32_e32 v25, 0xffff0000, v11
	s_ashr_i32 s7, s6, 31
	s_lshl_b64 s[6:7], s[6:7], 12
	v_mul_f32_e32 v21, 0x45800000, v20
	v_cndmask_b32_e32 v20, v20, v21, vcc
	v_pk_mul_f32 v[14:15], v[20:21], v[14:15] op_sel_hi:[0,1]
	v_pk_mul_f32 v[14:15], v[2:3], v[14:15]
	v_pk_mul_f32 v[18:19], v[20:21], v[18:19] op_sel_hi:[0,1]
	v_pk_mul_f32 v[14:15], v[14:15], v[24:25]
	v_pk_mul_f32 v[18:19], v[0:1], v[18:19]
	v_cvt_pk_bf16_f32 v11, v14, v15
	v_lshlrev_b32_e32 v14, 16, v10
	v_and_b32_e32 v15, 0xffff0000, v10
	v_pk_mul_f32 v[14:15], v[18:19], v[14:15]
	v_pk_mul_f32 v[12:13], v[20:21], v[12:13] op_sel_hi:[0,1]
	v_cvt_pk_bf16_f32 v10, v14, v15
	v_lshlrev_b32_e32 v14, 16, v9
	v_and_b32_e32 v15, 0xffff0000, v9
	v_pk_mul_f32 v[12:13], v[6:7], v[12:13]
	v_lshl_add_u64 v[22:23], v[70:71], 0, s[6:7]
	v_pk_mul_f32 v[12:13], v[12:13], v[14:15]
	v_pk_mul_f32 v[14:15], v[20:21], v[16:17] op_sel_hi:[0,1]
	v_cvt_pk_bf16_f32 v9, v12, v13
	v_lshlrev_b32_e32 v12, 16, v8
	v_and_b32_e32 v13, 0xffff0000, v8
	v_pk_mul_f32 v[14:15], v[4:5], v[14:15]
	s_nop 0
	v_pk_mul_f32 v[12:13], v[14:15], v[12:13]
	s_nop 0
	v_cvt_pk_bf16_f32 v8, v12, v13
	global_store_dwordx4 v[22:23], v[8:11], off
	s_branch .LBB0_179

.LBB0_258:
	s_andn2_b64 vcc, exec, s[0:1]
	s_cbranch_vccnz .LBB0_261
	s_cmpk_gt_u32 s39, 0xb7f
	s_cbranch_scc1 .LBB0_261
	v_add_u32_e32 v0, s38, v89
	v_add_u32_e32 v86, 0xffffe200, v0
	v_add_u32_e32 v80, 0xfffff200, v0
	v_ashrrev_i32_e32 v87, 31, v86
	v_lshlrev_b64 v[0:1], 13, v[86:87]
	v_ashrrev_i32_e32 v81, 31, v80
	v_lshl_add_u64 v[0:1], v[68:69], 0, v[0:1]
	v_lshlrev_b64 v[2:3], 13, v[80:81]
	v_lshl_add_u64 v[2:3], v[68:69], 0, v[2:3]
	global_load_dwordx4 v[104:107], v[70:71], off
	global_load_dwordx4 v[108:111], v[70:71], off offset:1024
	global_load_dwordx4 v[112:115], v[70:71], off offset:2048
	global_load_dwordx4 v[116:119], v[70:71], off offset:3072
	global_load_dwordx4 v[120:123], v[72:73], off
	global_load_dwordx4 v[124:127], v[74:75], off
	global_load_dwordx4 v[128:131], v[76:77], off
	global_load_dwordx4 v[132:135], v[78:79], off
	global_load_dwordx4 v[60:63], v[0:1], off nt
	global_load_dwordx4 v[56:59], v[2:3], off nt
	global_load_dwordx4 v[52:55], v[0:1], off offset:1024 nt
	global_load_dwordx4 v[48:51], v[2:3], off offset:1024 nt
	global_load_dwordx4 v[44:47], v[0:1], off offset:2048 nt
	global_load_dwordx4 v[40:43], v[2:3], off offset:2048 nt
	global_load_dwordx4 v[36:39], v[0:1], off offset:3072 nt
	global_load_dwordx4 v[32:35], v[2:3], off offset:3072 nt
	v_add_co_u32_e32 v0, vcc, s29, v0
	v_lshlrev_b64 v[86:87], 12, v[86:87]
	s_nop 0
	v_addc_co_u32_e32 v1, vcc, 0, v1, vcc
	global_load_dwordx4 v[28:31], v[0:1], off nt
	v_add_co_u32_e32 v2, vcc, s29, v2
	v_lshlrev_b64 v[80:81], 12, v[80:81]
	s_nop 0
	v_addc_co_u32_e32 v3, vcc, 0, v3, vcc
	global_load_dwordx4 v[24:27], v[2:3], off nt
	global_load_dwordx4 v[20:23], v[0:1], off offset:1024 nt
	global_load_dwordx4 v[16:19], v[2:3], off offset:1024 nt
	global_load_dwordx4 v[12:15], v[0:1], off offset:2048 nt
	global_load_dwordx4 v[8:11], v[2:3], off offset:2048 nt
	global_load_dwordx4 v[4:7], v[0:1], off offset:3072 nt
	s_nop 0
	global_load_dwordx4 v[0:3], v[2:3], off offset:3072 nt
	v_cmp_lt_i32_e32 vcc, v228, v227
	v_lshl_add_u64 v[86:87], v[66:67], 0, v[86:87]
	v_lshl_add_u64 v[80:81], v[66:67], 0, v[80:81]
	s_waitcnt vmcnt(15)
	v_mov_b32_e32 v95, v61
	s_waitcnt vmcnt(14)
	v_mov_b32_e32 v94, v57
	v_pk_mul_f32 v[94:95], v[94:95], v[94:95]
	s_waitcnt vmcnt(12)
	v_mov_b32_e32 v96, v49
	v_mov_b32_e32 v97, v53
	v_pk_mul_f32 v[96:97], v[96:97], v[96:97]
	s_waitcnt vmcnt(7)
	v_mov_b32_e32 v84, v29
	s_waitcnt vmcnt(5)
	v_mov_b32_e32 v85, v21
	v_mov_b32_e32 v82, v28
	v_mov_b32_e32 v83, v20
	v_pk_mul_f32 v[84:85], v[84:85], v[84:85]
	v_mov_b32_e32 v92, v25
	v_pk_fma_f32 v[82:83], v[82:83], v[82:83], v[84:85]
	v_mov_b32_e32 v84, v30
	v_mov_b32_e32 v85, v22
	v_pk_fma_f32 v[82:83], v[84:85], v[84:85], v[82:83]
	v_mov_b32_e32 v84, v31
	v_mov_b32_e32 v85, v23
	s_waitcnt vmcnt(4)
	v_mov_b32_e32 v93, v17
	v_pk_fma_f32 v[82:83], v[84:85], v[84:85], v[82:83]
	v_mov_b32_e32 v84, v24
	v_mov_b32_e32 v85, v16
	v_pk_mul_f32 v[92:93], v[92:93], v[92:93]
	s_waitcnt vmcnt(2)
	v_mov_b32_e32 v98, v9
	v_pk_fma_f32 v[84:85], v[84:85], v[84:85], v[92:93]
	v_mov_b32_e32 v92, v26
	v_mov_b32_e32 v93, v18
	v_pk_fma_f32 v[84:85], v[92:93], v[92:93], v[84:85]
	v_mov_b32_e32 v92, v27
	v_mov_b32_e32 v93, v19
	v_pk_fma_f32 v[84:85], v[92:93], v[92:93], v[84:85]
	v_mov_b32_e32 v92, v56
	v_mov_b32_e32 v93, v60
	v_pk_fma_f32 v[92:93], v[92:93], v[92:93], v[94:95]
	v_mov_b32_e32 v94, v58
	v_mov_b32_e32 v95, v62
	v_pk_fma_f32 v[92:93], v[94:95], v[94:95], v[92:93]
	v_mov_b32_e32 v94, v59
	v_mov_b32_e32 v95, v63
	v_pk_fma_f32 v[92:93], v[94:95], v[94:95], v[92:93]
	v_mov_b32_e32 v94, v48
	v_mov_b32_e32 v95, v52
	v_pk_fma_f32 v[94:95], v[94:95], v[94:95], v[96:97]
	v_mov_b32_e32 v96, v50
	v_mov_b32_e32 v97, v54
	v_pk_fma_f32 v[94:95], v[96:97], v[96:97], v[94:95]
	v_mov_b32_e32 v96, v51
	v_mov_b32_e32 v97, v55
	v_pk_fma_f32 v[94:95], v[96:97], v[96:97], v[94:95]
	v_mov_b32_e32 v96, v41
	v_mov_b32_e32 v97, v45
	v_pk_add_f32 v[92:93], v[92:93], v[94:95]
	v_mov_b32_e32 v94, v40
	v_mov_b32_e32 v95, v44
	v_pk_mul_f32 v[96:97], v[96:97], v[96:97]
	s_waitcnt vmcnt(0)
	v_mov_b32_e32 v99, v1
	v_pk_fma_f32 v[94:95], v[94:95], v[94:95], v[96:97]
	v_mov_b32_e32 v96, v42
	v_mov_b32_e32 v97, v46
	v_pk_fma_f32 v[94:95], v[96:97], v[96:97], v[94:95]
	v_mov_b32_e32 v96, v43
	v_mov_b32_e32 v97, v47
	v_pk_fma_f32 v[94:95], v[96:97], v[96:97], v[94:95]
	v_mov_b32_e32 v96, v33
	v_mov_b32_e32 v97, v37
	v_pk_add_f32 v[92:93], v[92:93], v[94:95]
	v_mov_b32_e32 v94, v32
	v_mov_b32_e32 v95, v36
	v_pk_mul_f32 v[96:97], v[96:97], v[96:97]
	v_pk_mul_f32 v[98:99], v[98:99], v[98:99]
	v_pk_fma_f32 v[94:95], v[94:95], v[94:95], v[96:97]
	v_mov_b32_e32 v96, v34
	v_mov_b32_e32 v97, v38
	v_pk_fma_f32 v[94:95], v[96:97], v[96:97], v[94:95]
	v_mov_b32_e32 v96, v35
	v_mov_b32_e32 v97, v39
	v_pk_fma_f32 v[94:95], v[96:97], v[96:97], v[94:95]
	v_mov_b32_e32 v96, v13
	v_pk_add_f32 v[92:93], v[92:93], v[94:95]
	v_mov_b32_e32 v94, v84
	v_mov_b32_e32 v95, v82
	v_mov_b32_e32 v97, v5
	v_pk_add_f32 v[92:93], v[92:93], v[94:95]
	v_mov_b32_e32 v94, v12
	v_mov_b32_e32 v95, v4
	v_pk_mul_f32 v[96:97], v[96:97], v[96:97]
	v_cndmask_b32_e32 v82, v226, v228, vcc
	v_pk_fma_f32 v[94:95], v[94:95], v[94:95], v[96:97]
	v_mov_b32_e32 v96, v14
	v_mov_b32_e32 v97, v6
	v_pk_fma_f32 v[94:95], v[96:97], v[96:97], v[94:95]
	v_mov_b32_e32 v96, v15
	v_mov_b32_e32 v97, v7
	v_pk_fma_f32 v[94:95], v[96:97], v[96:97], v[94:95]
	v_mov_b32_e32 v96, v8
	v_mov_b32_e32 v97, v0
	v_pk_fma_f32 v[96:97], v[96:97], v[96:97], v[98:99]
	v_mov_b32_e32 v98, v10
	v_mov_b32_e32 v99, v2
	v_cmp_lt_i32_e32 vcc, v229, v227
	v_pk_fma_f32 v[96:97], v[98:99], v[98:99], v[96:97]
	v_mov_b32_e32 v98, v11
	v_mov_b32_e32 v99, v3
	v_lshlrev_b32_e32 v91, 2, v82
	v_cndmask_b32_e32 v82, v226, v229, vcc
	v_cmp_lt_i32_e32 vcc, v230, v227
	v_pk_fma_f32 v[96:97], v[98:99], v[98:99], v[96:97]
	v_lshlrev_b32_e32 v98, 2, v82
	v_cndmask_b32_e32 v82, v226, v230, vcc
	v_cmp_lt_i32_e32 vcc, v231, v227
	v_lshlrev_b32_e32 v99, 2, v82
	v_mov_b32_e32 v84, v96
	v_cndmask_b32_e32 v82, v226, v231, vcc
	v_cmp_lt_i32_e32 vcc, v232, v227
	v_lshlrev_b32_e32 v100, 2, v82
	s_nop 0
	v_cndmask_b32_e32 v82, v226, v232, vcc
	v_cmp_lt_i32_e32 vcc, v233, v227
	v_lshlrev_b32_e32 v101, 2, v82
	s_nop 0
	v_cndmask_b32_e32 v82, v226, v233, vcc
	v_lshlrev_b32_e32 v102, 2, v82
	v_mov_b32_e32 v82, v85
	v_pk_add_f32 v[82:83], v[92:93], v[82:83]
	v_mov_b32_e32 v85, v94
	v_pk_add_f32 v[82:83], v[82:83], v[84:85]
	v_mov_b32_e32 v94, v97
	v_pk_add_f32 v[82:83], v[82:83], v[94:95]
	ds_bpermute_b32 v85, v91, v83
	ds_bpermute_b32 v84, v91, v82
	s_waitcnt lgkmcnt(0)
	v_pk_add_f32 v[82:83], v[82:83], v[84:85]
	ds_bpermute_b32 v85, v98, v83
	ds_bpermute_b32 v84, v98, v82
	s_waitcnt lgkmcnt(0)
	v_pk_add_f32 v[82:83], v[82:83], v[84:85]
	s_nop 1
	v_add_f32_dpp v82, v82, v82 row_mirror row_mask:0xf bank_mask:0xf
	v_add_f32_dpp v83, v83, v83 row_mirror row_mask:0xf bank_mask:0xf
	s_nop 1
	v_add_f32_dpp v82, v82, v82 row_half_mirror row_mask:0xf bank_mask:0xf
	v_add_f32_dpp v83, v83, v83 row_half_mirror row_mask:0xf bank_mask:0xf
	s_nop 1
	v_add_f32_dpp v82, v82, v82 quad_perm:[2,3,0,1] row_mask:0xf bank_mask:0xf
	v_add_f32_dpp v83, v83, v83 quad_perm:[2,3,0,1] row_mask:0xf bank_mask:0xf
	s_nop 1
	v_add_f32_dpp v82, v82, v82 quad_perm:[1,0,3,2] row_mask:0xf bank_mask:0xf
	v_add_f32_dpp v83, v83, v83 quad_perm:[1,0,3,2] row_mask:0xf bank_mask:0xf
	s_nop 0
	v_pk_fma_f32 v[82:83], v[82:83], s[34:35], v[188:189] op_sel_hi:[1,0,0]
	s_nop 0
	v_mul_f32_e32 v84, 0x4b800000, v83
	v_cmp_gt_f32_e64 s[10:11], s80, v83
	v_cmp_gt_f32_e32 vcc, s80, v82
	s_nop 0
	v_cndmask_b32_e64 v83, v83, v84, s[10:11]
	v_rsq_f32_e32 v83, v83
	s_nop 0
	v_mul_f32_e32 v84, 0x45800000, v83
	v_cndmask_b32_e64 v84, v83, v84, s[10:11]
	v_mul_f32_e32 v83, 0x4b800000, v82
	v_cndmask_b32_e32 v82, v82, v83, vcc
	v_rsq_f32_e32 v82, v82
	v_pk_mul_f32 v[60:61], v[60:61], v[84:85] op_sel_hi:[1,0]
	v_pk_mul_f32 v[62:63], v[62:63], v[84:85] op_sel_hi:[1,0]
	v_pk_mul_f32 v[52:53], v[52:53], v[84:85] op_sel_hi:[1,0]
	v_mul_f32_e32 v83, 0x45800000, v82
	v_cndmask_b32_e32 v82, v82, v83, vcc
	v_pk_mul_f32 v[56:57], v[56:57], v[82:83] op_sel_hi:[1,0]
	v_pk_mul_f32 v[58:59], v[58:59], v[82:83] op_sel_hi:[1,0]
	v_pk_mul_f32 v[54:55], v[54:55], v[84:85] op_sel_hi:[1,0]
	v_pk_mul_f32 v[48:49], v[48:49], v[82:83] op_sel_hi:[1,0]
	v_pk_mul_f32 v[50:51], v[50:51], v[82:83] op_sel_hi:[1,0]
	v_pk_mul_f32 v[44:45], v[44:45], v[84:85] op_sel_hi:[1,0]
	v_pk_mul_f32 v[46:47], v[46:47], v[84:85] op_sel_hi:[1,0]
	v_pk_mul_f32 v[40:41], v[40:41], v[82:83] op_sel_hi:[1,0]
	v_pk_mul_f32 v[42:43], v[42:43], v[82:83] op_sel_hi:[1,0]
	v_pk_mul_f32 v[36:37], v[36:37], v[84:85] op_sel_hi:[1,0]
	v_pk_mul_f32 v[38:39], v[38:39], v[84:85] op_sel_hi:[1,0]
	v_pk_mul_f32 v[32:33], v[32:33], v[82:83] op_sel_hi:[1,0]
	v_pk_mul_f32 v[34:35], v[34:35], v[82:83] op_sel_hi:[1,0]
	v_pk_mul_f32 v[28:29], v[28:29], v[84:85] op_sel_hi:[1,0]
	v_pk_mul_f32 v[30:31], v[30:31], v[84:85] op_sel_hi:[1,0]
	v_pk_mul_f32 v[24:25], v[24:25], v[82:83] op_sel_hi:[1,0]
	s_waitcnt vmcnt(0)
	v_pk_mul_f32 v[60:61], v[104:105], v[60:61]
	v_pk_mul_f32 v[62:63], v[106:107], v[62:63]
	v_pk_mul_f32 v[56:57], v[104:105], v[56:57]
	v_pk_mul_f32 v[58:59], v[106:107], v[58:59]
	v_cvt_pk_bf16_f32 v60, v60, v61
	v_cvt_pk_bf16_f32 v61, v62, v63
	v_cvt_pk_bf16_f32 v56, v56, v57
	v_cvt_pk_bf16_f32 v57, v58, v59
	global_store_dwordx2 v[86:87], v[60:61], off
	global_store_dwordx2 v[80:81], v[56:57], off
	v_pk_mul_f32 v[26:27], v[26:27], v[82:83] op_sel_hi:[1,0]
	v_pk_mul_f32 v[20:21], v[20:21], v[84:85] op_sel_hi:[1,0]
	v_pk_mul_f32 v[22:23], v[22:23], v[84:85] op_sel_hi:[1,0]
	v_pk_mul_f32 v[16:17], v[16:17], v[82:83] op_sel_hi:[1,0]
	v_pk_mul_f32 v[18:19], v[18:19], v[82:83] op_sel_hi:[1,0]
	v_pk_mul_f32 v[12:13], v[12:13], v[84:85] op_sel_hi:[1,0]
	v_pk_mul_f32 v[14:15], v[14:15], v[84:85] op_sel_hi:[1,0]
	v_pk_mul_f32 v[8:9], v[8:9], v[82:83] op_sel_hi:[1,0]
	v_pk_mul_f32 v[10:11], v[10:11], v[82:83] op_sel_hi:[1,0]
	v_pk_mul_f32 v[4:5], v[4:5], v[84:85] op_sel_hi:[1,0]
	v_pk_mul_f32 v[6:7], v[6:7], v[84:85] op_sel_hi:[1,0]
	v_pk_mul_f32 v[0:1], v[0:1], v[82:83] op_sel_hi:[1,0]
	v_pk_mul_f32 v[2:3], v[2:3], v[82:83] op_sel_hi:[1,0]
	v_pk_mul_f32 v[52:53], v[52:53], v[108:109]
	v_pk_mul_f32 v[54:55], v[54:55], v[110:111]
	v_pk_mul_f32 v[48:49], v[108:109], v[48:49]
	v_pk_mul_f32 v[50:51], v[50:51], v[110:111]
	v_cvt_pk_bf16_f32 v52, v52, v53
	v_cvt_pk_bf16_f32 v53, v54, v55
	v_cvt_pk_bf16_f32 v48, v48, v49
	v_cvt_pk_bf16_f32 v49, v50, v51
	global_store_dwordx2 v[86:87], v[52:53], off offset:512
	global_store_dwordx2 v[80:81], v[48:49], off offset:512
	v_pk_mul_f32 v[44:45], v[44:45], v[112:113]
	v_pk_mul_f32 v[46:47], v[46:47], v[114:115]
	v_pk_mul_f32 v[40:41], v[40:41], v[112:113]
	v_pk_mul_f32 v[42:43], v[42:43], v[114:115]
	v_cvt_pk_bf16_f32 v44, v44, v45
	v_cvt_pk_bf16_f32 v45, v46, v47
	v_cvt_pk_bf16_f32 v40, v40, v41
	v_cvt_pk_bf16_f32 v41, v42, v43
	global_store_dwordx2 v[86:87], v[44:45], off offset:1024
	global_store_dwordx2 v[80:81], v[40:41], off offset:1024
	v_pk_mul_f32 v[36:37], v[36:37], v[116:117]
	v_pk_mul_f32 v[38:39], v[38:39], v[118:119]
	v_pk_mul_f32 v[32:33], v[32:33], v[116:117]
	v_pk_mul_f32 v[34:35], v[34:35], v[118:119]
	v_cvt_pk_bf16_f32 v36, v36, v37
	v_cvt_pk_bf16_f32 v37, v38, v39
	v_cvt_pk_bf16_f32 v32, v32, v33
	v_cvt_pk_bf16_f32 v33, v34, v35
	global_store_dwordx2 v[86:87], v[36:37], off offset:1536
	global_store_dwordx2 v[80:81], v[32:33], off offset:1536
	v_pk_mul_f32 v[28:29], v[28:29], v[120:121]
	v_pk_mul_f32 v[30:31], v[30:31], v[122:123]
	v_pk_mul_f32 v[24:25], v[24:25], v[120:121]
	v_pk_mul_f32 v[26:27], v[26:27], v[122:123]
	v_cvt_pk_bf16_f32 v28, v28, v29
	v_cvt_pk_bf16_f32 v29, v30, v31
	v_cvt_pk_bf16_f32 v24, v24, v25
	v_cvt_pk_bf16_f32 v25, v26, v27
	global_store_dwordx2 v[86:87], v[28:29], off offset:2048
	global_store_dwordx2 v[80:81], v[24:25], off offset:2048
	v_pk_mul_f32 v[20:21], v[20:21], v[124:125]
	v_pk_mul_f32 v[22:23], v[22:23], v[126:127]
	v_pk_mul_f32 v[16:17], v[16:17], v[124:125]
	v_pk_mul_f32 v[18:19], v[18:19], v[126:127]
	v_cvt_pk_bf16_f32 v20, v20, v21
	v_cvt_pk_bf16_f32 v21, v22, v23
	v_cvt_pk_bf16_f32 v16, v16, v17
	v_cvt_pk_bf16_f32 v17, v18, v19
	global_store_dwordx2 v[86:87], v[20:21], off offset:2560
	global_store_dwordx2 v[80:81], v[16:17], off offset:2560
	v_pk_mul_f32 v[12:13], v[12:13], v[128:129]
	v_pk_mul_f32 v[14:15], v[14:15], v[130:131]
	v_pk_mul_f32 v[8:9], v[8:9], v[128:129]
	v_pk_mul_f32 v[10:11], v[10:11], v[130:131]
	v_cvt_pk_bf16_f32 v12, v12, v13
	v_cvt_pk_bf16_f32 v13, v14, v15
	v_cvt_pk_bf16_f32 v8, v8, v9
	v_cvt_pk_bf16_f32 v9, v10, v11
	global_store_dwordx2 v[86:87], v[12:13], off offset:3072
	global_store_dwordx2 v[80:81], v[8:9], off offset:3072
	v_pk_mul_f32 v[4:5], v[4:5], v[132:133]
	v_pk_mul_f32 v[6:7], v[6:7], v[134:135]
	v_pk_mul_f32 v[0:1], v[0:1], v[132:133]
	v_pk_mul_f32 v[2:3], v[2:3], v[134:135]
	v_cvt_pk_bf16_f32 v4, v4, v5
	v_cvt_pk_bf16_f32 v5, v6, v7
	v_cvt_pk_bf16_f32 v0, v0, v1
	v_cvt_pk_bf16_f32 v1, v2, v3
	global_store_dwordx2 v[86:87], v[4:5], off offset:3584
	global_store_dwordx2 v[80:81], v[0:1], off offset:3584
